# EW reductions: first four butterfly hops (xor 1,2,4,8) as DPP adds instead of ds_bpermute round trips (bit-identical sums)
# speedup vs baseline: 1.0747x; 1.0020x over previous
; __device__ __forceinline__ float bf_lo(unsigned w) { return __uint_as_float(w << 16); }
; __device__ __forceinline__ float bf_hi(unsigned w) { return __uint_as_float(w & 0xffff0000u); }
; __device__ __forceinline__ float wave_sum(float v) {
; #pragma unroll
;     for (int o = 1; o < 64; o <<= 1) v += __shfl_xor(v, o);
;     return v;
; __device__ __forceinline__ void ew_phase(const Frame& F, const bf16_t* f, const float* gpost, float alpha, const float* hin, float* hout, const float* gpre, bf16_t* xn, ...
;     ...
;     for (int it_ = 0; it_ < it_n; ++it_) {
;         const int m = prow0 >= 0 ? prow0 + F.wave * 8 + it_ : F.gw + it_ * F.NGW; if (m >= T) break;
;         const u32x2* fr = (const u32x2*)(f + (size_t)m * DM) + F.lane; const f32x4* hr = (const f32x4*)(hin + (size_t)m * DM) + F.lane;
;         f32x4 fv[4], hv[4]; float s = 0.f;
; #pragma unroll
;         for (int j = 0; j < 4; ++j) { const u32x2 w = fr[64 * j]; hv[j] = in24 ? load24(h24 + (size_t)m * (DM * 3), F.lane + 64 * j) : hr[64 * j]; fv[j] = (f32x4){bf_lo(w.x), bf_hi(w.x), bf_lo(w.y), bf_hi(w.y)};
;             s += (fv[j].x * fv[j].x + fv[j].y * fv[j].y) + (fv[j].z * fv[j].z + fv[j].w * fv[j].w); }
;         const float rstd = alpha / sqrtf(wave_sum(s) * (1.f / DM) + RMS_EPS);
.LBB0_209:
	v_readlane_b32 s0, v252, 11
	s_add_i32 s2, s14, s9
	v_readlane_b32 s1, v252, 12
	s_and_b64 s[0:1], s[0:1], exec
	s_cselect_b32 s10, s2, s15
	s_cmpk_gt_i32 s10, 0x3fff
	s_mov_b64 s[0:1], -1
	s_cbranch_scc1 .LBB0_208
	s_ashr_i32 s11, s10, 31
	s_lshl_b64 s[12:13], s[10:11], 11
	s_mul_i32 s0, s10, 0xc00
	s_mul_hi_i32 s1, s10, 0xc00
	s_add_u32 s0, s24, s0
	s_addc_u32 s1, s25, s1
	v_lshl_add_u64 v[70:71], v[34:35], 0, s[12:13]
	v_lshl_add_u64 v[54:55], s[0:1], 0, v[38:39]
	v_lshl_add_u64 v[64:65], s[0:1], 0, v[40:41]
	v_lshl_add_u64 v[162:163], s[0:1], 0, v[44:45]
	v_lshl_add_u64 v[164:165], s[0:1], 0, v[46:47]
	global_load_dwordx2 v[62:63], v[70:71], off
	global_load_dwordx2 v[58:59], v[54:55], off
	global_load_dwordx2 v[60:61], v[54:55], off offset:4
	global_load_dwordx2 v[72:73], v[70:71], off offset:512
	global_load_dwordx2 v[68:69], v[64:65], off
	global_load_dwordx2 v[74:75], v[64:65], off offset:4
	global_load_dwordx2 v[78:79], v[70:71], off offset:1024
	global_load_dwordx2 v[82:83], v[162:163], off
	global_load_dwordx2 v[84:85], v[162:163], off offset:4
	global_load_dwordx2 v[86:87], v[70:71], off offset:1536
	global_load_dwordx2 v[166:167], v[164:165], off
	global_load_dwordx2 v[88:89], v[164:165], off offset:4
	s_mov_b32 s2, 0xff00
	s_waitcnt vmcnt(10)
	v_lshrrev_b32_e32 v59, 8, v59
	s_waitcnt vmcnt(9) lgkmcnt(0)
	v_lshlrev_b32_e32 v0, 24, v61
	v_lshlrev_b32_e32 v57, 16, v60
	v_and_b32_e32 v59, 0xffff00, v59
	v_and_b32_sdwa v60, v58, s2 dst_sel:DWORD dst_unused:UNUSED_PAD src0_sel:WORD_1 src1_sel:DWORD
	v_lshlrev_b32_e32 v56, 8, v58
	v_or_b32_e32 v58, v0, v59
	v_or_b32_e32 v57, v57, v60
	v_and_b32_e32 v59, 0xffffff00, v61
	v_lshlrev_b32_e32 v60, 16, v62
	v_and_b32_e32 v61, 0xffff0000, v62
	v_lshlrev_b32_e32 v62, 16, v63
	v_and_b32_e32 v63, 0xffff0000, v63
	v_mul_f32_e32 v0, v63, v63
	s_waitcnt vmcnt(7)
	v_lshrrev_b32_e32 v69, 8, v69
	v_pk_fma_f32 v[96:97], v[62:63], v[62:63], v[0:1] op_sel_hi:[1,1,0]
	s_waitcnt vmcnt(6)
	v_lshlrev_b32_e32 v0, 24, v75
	v_lshlrev_b32_e32 v67, 16, v74
	v_and_b32_e32 v69, 0xffff00, v69
	v_and_b32_sdwa v74, v68, s2 dst_sel:DWORD dst_unused:UNUSED_PAD src0_sel:WORD_1 src1_sel:DWORD
	v_lshlrev_b32_e32 v66, 8, v68
	v_or_b32_e32 v68, v0, v69
	v_or_b32_e32 v67, v67, v74
	v_and_b32_e32 v69, 0xffffff00, v75
	v_lshlrev_b32_e32 v75, 16, v73
	v_lshlrev_b32_e32 v74, 16, v72
	v_and_b32_e32 v73, 0xffff0000, v73
	v_and_b32_e32 v72, 0xffff0000, v72
	v_pk_mul_f32 v[76:77], v[72:73], v[72:73]
	s_waitcnt vmcnt(5)
	v_lshlrev_b32_e32 v92, 16, v78
	v_pk_fma_f32 v[100:101], v[74:75], v[74:75], v[76:77]
	v_lshl_add_u64 v[76:77], s[0:1], 0, v[44:45]
	v_lshl_add_u64 v[70:71], s[0:1], 0, v[46:47]
	v_and_b32_e32 v93, 0xffff0000, v78
	v_lshlrev_b32_e32 v94, 16, v79
	v_and_b32_e32 v95, 0xffff0000, v79
	v_mov_b32_e32 v104, v96
	v_pk_add_f32 v[100:101], v[100:101], v[100:101] op_sel:[0,1] op_sel_hi:[1,0]
	s_waitcnt vmcnt(4)
	v_lshrrev_b32_e32 v83, 8, v83
	v_lshlrev_b32_e32 v80, 8, v82
	s_waitcnt vmcnt(3)
	v_lshlrev_b32_e32 v0, 24, v85
	v_lshlrev_b32_e32 v81, 16, v84
	v_and_b32_e32 v83, 0xffff00, v83
	v_and_b32_sdwa v82, v82, s2 dst_sel:DWORD dst_unused:UNUSED_PAD src0_sel:WORD_1 src1_sel:DWORD
	v_or_b32_e32 v84, v0, v83
	v_or_b32_e32 v81, v81, v82
	s_waitcnt vmcnt(2)
	v_lshlrev_b32_e32 v91, 16, v86
	v_mov_b32_e32 v105, v91
	v_and_b32_e32 v85, 0xffffff00, v85
	s_waitcnt vmcnt(1)
	v_lshrrev_b32_e32 v83, 8, v167
	s_waitcnt vmcnt(0)
	v_lshlrev_b32_e32 v0, 24, v89
	v_and_b32_e32 v83, 0xffff00, v83
	v_lshlrev_b32_e32 v78, 8, v166
	v_lshlrev_b32_e32 v79, 16, v88
	v_and_b32_sdwa v88, v166, s2 dst_sel:DWORD dst_unused:UNUSED_PAD src0_sel:WORD_1 src1_sel:DWORD
	v_or_b32_e32 v82, v0, v83
	v_mul_f32_e32 v0, v61, v61
	v_pk_fma_f32 v[102:103], v[60:61], v[60:61], v[0:1] op_sel_hi:[1,1,0]
	v_and_b32_e32 v83, 0xffffff00, v89
	v_and_b32_e32 v89, 0xffff0000, v86
	v_mov_b32_e32 v90, v102
	v_or_b32_e32 v79, v79, v88
	v_mul_f32_e32 v88, v89, v89
	v_pk_add_f32 v[96:97], v[102:103], v[96:97]
	v_pk_mul_f32 v[102:103], v[90:91], v[104:105]
	v_mov_b32_e32 v101, v88
	v_mov_b32_e32 v97, v103
	v_mul_f32_e32 v0, v93, v93
	v_lshlrev_b32_e32 v86, 16, v87
	v_and_b32_e32 v87, 0xffff0000, v87
	v_pk_add_f32 v[96:97], v[96:97], v[100:101]
	v_pk_fma_f32 v[100:101], v[92:93], v[92:93], v[0:1] op_sel_hi:[1,1,0]
	v_mul_f32_e32 v0, v95, v95
	v_mul_f32_e32 v99, v86, v86
	v_mul_f32_e32 v106, v87, v87
	v_pk_fma_f32 v[102:103], v[94:95], v[94:95], v[0:1] op_sel_hi:[1,1,0]
	v_mov_b32_e32 v101, v99
	v_mov_b32_e32 v103, v106
	v_pk_add_f32 v[100:101], v[100:101], v[102:103]
	v_and_b32_e32 v0, 64, v230
	v_pk_add_f32 v[96:97], v[96:97], v[100:101]
	v_add_u32_e32 v100, 64, v0
	v_xor_b32_e32 v0, 1, v230
	v_cmp_lt_i32_e32 vcc, v0, v100
	v_add_f32_e32 v88, v96, v97
	s_mov_b32 s2, 0xf800000
	v_cndmask_b32_e32 v0, v230, v0, vcc
	v_lshlrev_b32_e32 v0, 2, v0
	s_nop 1
	v_add_f32_dpp v88, v88, v88 quad_perm:[1,0,3,2] row_mask:0xf bank_mask:0xf
	v_xor_b32_e32 v90, 2, v230
	v_cmp_lt_i32_e32 vcc, v90, v100
	s_nop 1
	v_cndmask_b32_e32 v90, v230, v90, vcc
	v_lshlrev_b32_e32 v90, 2, v90
	s_nop 1
	v_add_f32_dpp v88, v88, v88 quad_perm:[2,3,0,1] row_mask:0xf bank_mask:0xf
	v_xor_b32_e32 v96, 4, v230
	v_cmp_lt_i32_e32 vcc, v96, v100
	s_nop 1
	v_cndmask_b32_e32 v96, v230, v96, vcc
	v_lshlrev_b32_e32 v96, 2, v96
	s_nop 1
	v_add_f32_dpp v88, v88, v88 row_half_mirror row_mask:0xf bank_mask:0xf
	v_xor_b32_e32 v97, 8, v230
	v_cmp_lt_i32_e32 vcc, v97, v100
	s_nop 1
	v_cndmask_b32_e32 v97, v230, v97, vcc
	v_lshlrev_b32_e32 v97, 2, v97
	s_nop 1
	v_add_f32_dpp v88, v88, v88 row_mirror row_mask:0xf bank_mask:0xf
	v_xor_b32_e32 v99, 16, v230
	v_cmp_lt_i32_e32 vcc, v99, v100
	s_nop 1
	v_cndmask_b32_e32 v99, v230, v99, vcc
	v_lshlrev_b32_e32 v99, 2, v99
	ds_bpermute_b32 v101, v99, v88
	s_waitcnt lgkmcnt(0)
; __device__ __forceinline__ void ew_phase(const Frame& F, const bf16_t* f, const float* gpost, float alpha, const float* hin, float* hout, const float* gpre, bf16_t* xn, ...
;     ...
;         const float rstd = alpha / sqrtf(wave_sum(s) * (1.f / DM) + RMS_EPS);
;         float s2 = 0.f; f32x4* ho = (f32x4*)(hout + (size_t)m * DM) + F.lane;
; #pragma unroll
;         for (int j = 0; j < 4; ++j) { hv[j] = hv[j] + fv[j] * rstd * gp[j]; if (out24) store24(h24 + (size_t)m * (DM * 3), F.lane + 64 * j, hv[j]); else ho[64 * j] = hv[j]; s2 += (hv[j].x * hv[j].x + hv[j].y * hv[j].y) + (hv[j].z * hv[j].z + hv[j].w * hv[j].w); }
;         if (gpre) {
;             const float r2 = 1.0f / sqrtf(wave_sum(s2) * (1.f / DM) + RMS_EPS);
	v_add_f32_e32 v88, v88, v101
	v_xor_b32_e32 v101, 32, v230
	v_cmp_lt_i32_e32 vcc, v101, v100
	s_nop 1
	v_cndmask_b32_e32 v100, v230, v101, vcc
	v_lshlrev_b32_e32 v100, 2, v100
	ds_bpermute_b32 v101, v100, v88
	s_waitcnt lgkmcnt(0)
	v_add_f32_e32 v88, v88, v101
	v_fmamk_f32 v88, v88, 0x3a800000, v225
	v_cmp_gt_f32_e32 vcc, s2, v88
	v_mul_f32_e32 v101, 0x4f800000, v88
	s_nop 0
	v_cndmask_b32_e32 v88, v88, v101, vcc
	v_sqrt_f32_e32 v101, v88
	s_nop 0
	v_add_u32_e32 v102, -1, v101
	v_fma_f32 v103, -v102, v101, v88
	v_cmp_ge_f32_e64 s[0:1], 0, v103
	v_add_u32_e32 v103, 1, v101
	s_nop 0
	v_cndmask_b32_e64 v102, v101, v102, s[0:1]
	v_fma_f32 v101, -v103, v101, v88
	v_cmp_lt_f32_e64 s[0:1], 0, v101
	s_nop 1
	v_cndmask_b32_e64 v101, v102, v103, s[0:1]
	v_mul_f32_e32 v102, 0x37800000, v101
	v_cndmask_b32_e32 v101, v101, v102, vcc
	v_cmp_class_f32_e32 vcc, v88, v226
	s_nop 1
	v_cndmask_b32_e32 v88, v101, v88, vcc
	v_div_scale_f32 v101, s[0:1], v88, v88, 0.5
	v_rcp_f32_e32 v102, v101
	s_movk_i32 s0, 0x7f
	s_mov_b32 s1, 0x7060503
	v_fma_f32 v103, -v101, v102, 1.0
	v_fmac_f32_e32 v102, v103, v102
	v_div_scale_f32 v103, vcc, 0.5, v88, 0.5
	v_mul_f32_e32 v104, v103, v102
	v_fma_f32 v105, -v101, v104, v103
	v_fmac_f32_e32 v104, v105, v102
	v_fma_f32 v101, -v101, v104, v103
	v_div_fmas_f32 v101, v101, v102, v104
	v_div_fixup_f32 v102, v101, v88, 0.5
	v_pk_mul_f32 v[60:61], v[102:103], v[60:61] op_sel_hi:[0,1]
	v_pk_mul_f32 v[62:63], v[102:103], v[62:63] op_sel_hi:[0,1]
	v_pk_fma_f32 v[58:59], v[4:5], v[62:63], v[58:59]
	v_pk_fma_f32 v[56:57], v[2:3], v[60:61], v[56:57]
	v_bfe_u32 v63, v58, 8, 1
	v_bfe_u32 v61, v57, 8, 1
	v_bfe_u32 v60, v56, 8, 1
	v_add3_u32 v61, v57, v61, s0
	v_add3_u32 v63, v58, v63, s0
	v_bfe_u32 v101, v59, 8, 1
	v_add3_u32 v60, v56, v60, s0
	v_lshrrev_b32_e32 v62, 8, v61
	v_lshrrev_b32_e32 v88, 8, v63
	v_add3_u32 v101, v59, v101, s0
	v_alignbit_b32 v60, v62, v60, 8
	v_alignbit_b32 v61, v88, v61, 16
	v_perm_b32 v62, v101, v63, s1
	global_store_dwordx3 v[54:55], v[60:62], off
	v_pk_mul_f32 v[54:55], v[58:59], v[58:59]
	v_mov_b32_e32 v88, v91
	v_pk_mul_f32 v[60:61], v[56:57], v[56:57]
	s_nop 0
	v_pk_mov_b32 v[62:63], v[60:61], v[54:55] op_sel:[1,0]
	v_mov_b32_e32 v61, v55
	v_pk_add_f32 v[54:55], v[60:61], v[62:63]
	s_nop 0
	v_pk_add_f32 v[62:63], v[54:55], v[54:55] op_sel_hi:[0,1]
	v_mov_b32_e32 v54, v74
	v_mov_b32_e32 v55, v72
	v_mov_b32_e32 v72, v75
	v_pk_mul_f32 v[60:61], v[102:103], v[54:55] op_sel_hi:[0,1]
	v_pk_mul_f32 v[54:55], v[102:103], v[72:73] op_sel_hi:[0,1]
	v_pk_fma_f32 v[54:55], v[8:9], v[54:55], v[68:69]
	v_pk_fma_f32 v[60:61], v[6:7], v[60:61], v[66:67]
	v_bfe_u32 v68, v54, 8, 1
	v_bfe_u32 v66, v61, 8, 1
	v_bfe_u32 v62, v60, 8, 1
	v_add3_u32 v67, v61, v66, s0
	v_add3_u32 v68, v54, v68, s0
	v_bfe_u32 v72, v55, 8, 1
	v_add3_u32 v62, v60, v62, s0
	v_lshrrev_b32_e32 v66, 8, v67
	v_lshrrev_b32_e32 v69, 8, v68
	v_add3_u32 v72, v55, v72, s0
	v_alignbit_b32 v66, v66, v62, 8
	v_alignbit_b32 v67, v69, v67, 16
	v_perm_b32 v68, v72, v68, s1
	global_store_dwordx3 v[64:65], v[66:68], off
	v_pk_mul_f32 v[64:65], v[54:55], v[54:55]
	s_nop 0
	v_pk_mul_f32 v[66:67], v[60:61], v[60:61]
	s_nop 0
	v_pk_mov_b32 v[68:69], v[66:67], v[64:65] op_sel:[1,0]
	v_mov_b32_e32 v67, v65
	v_pk_add_f32 v[64:65], v[66:67], v[68:69]
	v_pk_mul_f32 v[66:67], v[102:103], v[92:93] op_sel_hi:[0,1]
	v_pk_add_f32 v[68:69], v[64:65], v[64:65] op_sel_hi:[0,1]
	v_pk_mul_f32 v[64:65], v[102:103], v[94:95] op_sel_hi:[0,1]
	v_pk_fma_f32 v[64:65], v[20:21], v[64:65], v[84:85]
	v_pk_fma_f32 v[72:73], v[18:19], v[66:67], v[80:81]
	v_bfe_u32 v68, v64, 8, 1
	v_bfe_u32 v66, v73, 8, 1
	v_bfe_u32 v62, v72, 8, 1
	v_add3_u32 v67, v73, v66, s0
	v_add3_u32 v68, v64, v68, s0
	v_bfe_u32 v75, v65, 8, 1
	v_add3_u32 v62, v72, v62, s0
	v_lshrrev_b32_e32 v66, 8, v67
	v_lshrrev_b32_e32 v74, 8, v68
	v_add3_u32 v75, v65, v75, s0
	v_alignbit_b32 v66, v66, v62, 8
	v_alignbit_b32 v67, v74, v67, 16
	v_perm_b32 v68, v75, v68, s1
	global_store_dwordx3 v[76:77], v[66:68], off
	v_pk_mul_f32 v[74:75], v[86:87], v[102:103] op_sel_hi:[1,0]
	v_mul_f32_e32 v62, v72, v72
	v_pk_mul_f32 v[66:67], v[88:89], v[102:103] op_sel_hi:[1,0]
	v_pk_fma_f32 v[74:75], v[24:25], v[74:75], v[82:83]
	v_pk_fma_f32 v[76:77], v[22:23], v[66:67], v[78:79]
	v_pk_fma_f32 v[80:81], v[72:73], v[72:73], v[62:63] op_sel_hi:[1,1,0]
	v_mul_f32_e32 v62, v64, v64
	v_bfe_u32 v66, v77, 8, 1
	v_bfe_u32 v68, v74, 8, 1
	v_pk_fma_f32 v[84:85], v[64:65], v[64:65], v[62:63] op_sel_hi:[1,1,0]
	v_bfe_u32 v62, v76, 8, 1
	v_add3_u32 v67, v77, v66, s0
	v_add3_u32 v68, v74, v68, s0
	v_bfe_u32 v79, v75, 8, 1
	v_add3_u32 v62, v76, v62, s0
	v_lshrrev_b32_e32 v66, 8, v67
	v_lshrrev_b32_e32 v78, 8, v68
	v_add3_u32 v79, v75, v79, s0
	v_alignbit_b32 v66, v66, v62, 8
	v_alignbit_b32 v67, v78, v67, 16
	v_perm_b32 v68, v79, v68, s1
	global_store_dwordx3 v[70:71], v[66:68], off
	v_mul_f32_e32 v80, v76, v76
	v_mul_f32_e32 v84, v77, v77
	v_mul_f32_e32 v62, v75, v75
	v_mul_f32_e32 v68, v74, v74
	v_pk_add_f32 v[66:67], v[80:81], v[84:85]
	v_pk_add_f32 v[62:63], v[62:63], v[68:69]
	v_lshl_add_u64 v[78:79], v[36:37], 0, s[12:13]
	v_pk_add_f32 v[62:63], v[66:67], v[62:63]
	s_nop 0
	v_add_f32_e32 v62, v62, v63
	s_nop 1
	v_add_f32_dpp v62, v62, v62 quad_perm:[1,0,3,2] row_mask:0xf bank_mask:0xf
	s_nop 1
	v_add_f32_dpp v62, v62, v62 quad_perm:[2,3,0,1] row_mask:0xf bank_mask:0xf
	s_nop 1
	v_add_f32_dpp v62, v62, v62 row_half_mirror row_mask:0xf bank_mask:0xf
	s_nop 1
	v_add_f32_dpp v62, v62, v62 row_mirror row_mask:0xf bank_mask:0xf
	ds_bpermute_b32 v63, v99, v62
	s_waitcnt lgkmcnt(0)
	v_add_f32_e32 v62, v62, v63
	ds_bpermute_b32 v63, v100, v62
	s_waitcnt lgkmcnt(0)
; #define LAS __attribute__((address_space(3)))
; __device__ __forceinline__ unsigned cvt_pk_bf16(float lo, float hi) { f32x2 v = {lo, hi}; bf16x2_t b = __builtin_convertvector(v, bf16x2_t); return __builtin_bit_cast(unsigned, b); }
; __device__ __forceinline__ void ew_phase(const Frame& F, const bf16_t* f, const float* gpost, float alpha, const float* hin, float* hout, const float* gpre, bf16_t* xn, ...
;     ...
;             const float r2 = 1.0f / sqrtf(wave_sum(s2) * (1.f / DM) + RMS_EPS);
;             u32x2* o8 = (u32x2*)(xn + (size_t)m * DM) + F.lane;
; #pragma unroll
;             for (int j = 0; j < 4; ++j) { hv[j] = hv[j] * r2 * gq[j]; u32x2 w; w.x = cvt_pk_bf16(hv[j].x, hv[j].y); w.y = cvt_pk_bf16(hv[j].z, hv[j].w); o8[64 * j] = w; }
;             if (win_l) {
;                 float a8[8];
; #pragma unroll
;                 for (int k = 0; k < 8; ++k) a8[k] = 0.f;
; #pragma unroll
;                 for (int k = 0; k < 8; ++k)
; #pragma unroll
;                     for (int j = 0; j < 4; ++j) { const f32x4 w4 = *(const LAS f32x4*)(WF + k * DM + 256 * j + 4 * F.lane);
;                         a8[k] += (hv[j].x * w4.x + hv[j].y * w4.y) + (hv[j].z * w4.z + hv[j].w * w4.w); }
	v_add_f32_e32 v62, v62, v63
	v_fmamk_f32 v62, v62, 0x3a800000, v225
	v_cmp_gt_f32_e32 vcc, s2, v62
	v_mul_f32_e32 v63, 0x4f800000, v62
	s_nop 0
	v_cndmask_b32_e32 v62, v62, v63, vcc
	v_sqrt_f32_e32 v63, v62
	s_nop 0
	v_add_u32_e32 v66, -1, v63
	v_fma_f32 v67, -v66, v63, v62
	v_cmp_ge_f32_e64 s[0:1], 0, v67
	v_add_u32_e32 v67, 1, v63
	s_nop 0
	v_cndmask_b32_e64 v66, v63, v66, s[0:1]
	v_fma_f32 v63, -v67, v63, v62
	v_cmp_lt_f32_e64 s[0:1], 0, v63
	s_nop 1
	v_cndmask_b32_e64 v63, v66, v67, s[0:1]
	v_mul_f32_e32 v66, 0x37800000, v63
	v_cndmask_b32_e32 v63, v63, v66, vcc
	v_cmp_class_f32_e32 vcc, v62, v226
	s_nop 1
	v_cndmask_b32_e32 v62, v63, v62, vcc
	v_div_scale_f32 v63, s[0:1], v62, v62, 1.0
	v_rcp_f32_e32 v66, v63
	s_nop 0
	v_fma_f32 v67, -v63, v66, 1.0
	v_fmac_f32_e32 v66, v67, v66
	v_div_scale_f32 v67, vcc, 1.0, v62, 1.0
	v_mul_f32_e32 v68, v67, v66
	v_fma_f32 v69, -v63, v68, v67
	v_fmac_f32_e32 v68, v69, v66
	v_fma_f32 v63, -v63, v68, v67
	v_div_fmas_f32 v63, v63, v66, v68
	v_div_fixup_f32 v70, v63, v62, 1.0
	v_pk_mul_f32 v[56:57], v[56:57], v[70:71] op_sel_hi:[1,0]
	v_pk_mul_f32 v[58:59], v[58:59], v[70:71] op_sel_hi:[1,0]
	v_pk_mul_f32 v[68:69], v[10:11], v[56:57]
	v_pk_mul_f32 v[66:67], v[12:13], v[58:59]
	v_cvt_pk_bf16_f32 v56, v68, v69
	v_cvt_pk_bf16_f32 v57, v66, v67
	global_store_dwordx2 v[78:79], v[56:57], off
	v_pk_mul_f32 v[56:57], v[60:61], v[70:71] op_sel_hi:[1,0]
	v_pk_mul_f32 v[54:55], v[54:55], v[70:71] op_sel_hi:[1,0]
	v_pk_mul_f32 v[62:63], v[14:15], v[56:57]
	v_pk_mul_f32 v[58:59], v[16:17], v[54:55]
	v_cvt_pk_bf16_f32 v54, v62, v63
	v_cvt_pk_bf16_f32 v55, v58, v59
	global_store_dwordx2 v[78:79], v[54:55], off offset:512
	v_pk_mul_f32 v[54:55], v[72:73], v[70:71] op_sel_hi:[1,0]
	v_pk_mul_f32 v[56:57], v[64:65], v[70:71] op_sel_hi:[1,0]
	v_pk_mul_f32 v[64:65], v[26:27], v[54:55]
	v_pk_mul_f32 v[60:61], v[28:29], v[56:57]
	v_cvt_pk_bf16_f32 v54, v64, v65
	v_cvt_pk_bf16_f32 v55, v60, v61
	global_store_dwordx2 v[78:79], v[54:55], off offset:1024
	v_pk_mul_f32 v[56:57], v[76:77], v[70:71] op_sel_hi:[1,0]
	v_pk_mul_f32 v[54:55], v[74:75], v[70:71] op_sel_hi:[1,0]
	v_pk_mul_f32 v[56:57], v[30:31], v[56:57]
	v_pk_mul_f32 v[54:55], v[32:33], v[54:55]
	v_cvt_pk_bf16_f32 v70, v56, v57
	v_cvt_pk_bf16_f32 v71, v54, v55
	global_store_dwordx2 v[78:79], v[70:71], off offset:1536
	v_add_u32_e32 v70, 0, v43
	v_add_u32_e32 v70, 0x18000, v70
	ds_read_b128 v[72:75], v70
	s_waitcnt lgkmcnt(0)
	v_mul_f32_e32 v71, v73, v69
	v_fmac_f32_e32 v71, v72, v68
	v_mul_f32_e32 v72, v75, v67
	v_fmac_f32_e32 v72, v74, v66
	v_add_f32_e32 v71, v71, v72
	ds_read_b128 v[72:75], v70 offset:1024
	v_add_f32_e32 v71, 0, v71
	s_waitcnt lgkmcnt(0)
	v_mul_f32_e32 v73, v73, v63
	v_fmac_f32_e32 v73, v72, v62
	v_mul_f32_e32 v72, v75, v59
	v_fmac_f32_e32 v72, v74, v58
	v_add_f32_e32 v72, v73, v72
	v_add_f32_e32 v71, v72, v71
	ds_read_b128 v[72:75], v70 offset:2048
	s_waitcnt lgkmcnt(0)
	v_mul_f32_e32 v73, v73, v65
	v_fmac_f32_e32 v73, v72, v64
	v_mul_f32_e32 v72, v75, v61
	v_fmac_f32_e32 v72, v74, v60
	v_add_f32_e32 v72, v73, v72
	v_add_f32_e32 v71, v72, v71
	ds_read_b128 v[72:75], v70 offset:3072
	s_waitcnt lgkmcnt(0)
	v_mul_f32_e32 v73, v73, v57
	v_fmac_f32_e32 v73, v72, v56
	v_mul_f32_e32 v72, v75, v55
	v_fmac_f32_e32 v72, v74, v54
	v_add_f32_e32 v72, v73, v72
	v_add_f32_e32 v71, v72, v71
	ds_read_b128 v[72:75], v70 offset:4096
	s_waitcnt lgkmcnt(0)
	v_mul_f32_e32 v73, v73, v69
	v_fmac_f32_e32 v73, v72, v68
	v_mul_f32_e32 v72, v75, v67
	v_fmac_f32_e32 v72, v74, v66
	v_add_f32_e32 v72, v73, v72
	v_add_f32_e32 v76, 0, v72
	ds_read_b128 v[72:75], v70 offset:5120
	s_waitcnt lgkmcnt(0)
	v_mul_f32_e32 v73, v73, v63
	v_fmac_f32_e32 v73, v72, v62
	v_mul_f32_e32 v72, v75, v59
	v_fmac_f32_e32 v72, v74, v58
	v_add_f32_e32 v72, v73, v72
	v_add_f32_e32 v76, v72, v76
	ds_read_b128 v[72:75], v70 offset:6144
	s_waitcnt lgkmcnt(0)
	v_mul_f32_e32 v73, v73, v65
	v_fmac_f32_e32 v73, v72, v64
	v_mul_f32_e32 v72, v75, v61
	v_fmac_f32_e32 v72, v74, v60
	v_add_f32_e32 v72, v73, v72
	v_add_f32_e32 v76, v72, v76
	ds_read_b128 v[72:75], v70 offset:7168
	s_waitcnt lgkmcnt(0)
	v_mul_f32_e32 v73, v73, v57
	v_fmac_f32_e32 v73, v72, v56
	v_mul_f32_e32 v72, v75, v55
	v_fmac_f32_e32 v72, v74, v54
	v_add_f32_e32 v72, v73, v72
	v_add_f32_e32 v72, v72, v76
	ds_read_b128 v[74:77], v70 offset:8192
	s_waitcnt lgkmcnt(0)
	v_mul_f32_e32 v73, v75, v69
	v_fmac_f32_e32 v73, v74, v68
	v_mul_f32_e32 v74, v77, v67
	v_fmac_f32_e32 v74, v76, v66
	v_add_f32_e32 v73, v73, v74
	ds_read_b128 v[74:77], v70 offset:9216
	v_add_f32_e32 v73, 0, v73
	s_waitcnt lgkmcnt(0)
	v_mul_f32_e32 v75, v63, v75
	v_fmac_f32_e32 v75, v62, v74
	v_mul_f32_e32 v74, v59, v77
	v_fmac_f32_e32 v74, v58, v76
	v_add_f32_e32 v74, v75, v74
	v_add_f32_e32 v73, v74, v73
	ds_read_b128 v[74:77], v70 offset:10240
	s_waitcnt lgkmcnt(0)
	v_mul_f32_e32 v75, v65, v75
	v_fmac_f32_e32 v75, v64, v74
	v_mul_f32_e32 v74, v61, v77
	v_fmac_f32_e32 v74, v60, v76
	v_add_f32_e32 v74, v75, v74
	v_add_f32_e32 v73, v74, v73
	ds_read_b128 v[74:77], v70 offset:11264
	s_waitcnt lgkmcnt(0)
	v_mul_f32_e32 v75, v57, v75
	v_fmac_f32_e32 v75, v56, v74
	v_mul_f32_e32 v74, v55, v77
	v_fmac_f32_e32 v74, v54, v76
	v_add_f32_e32 v74, v75, v74
	v_add_f32_e32 v73, v74, v73
	ds_read_b128 v[74:77], v70 offset:12288
	s_waitcnt lgkmcnt(0)
	v_mul_f32_e32 v75, v69, v75
	v_fmac_f32_e32 v75, v68, v74
	v_mul_f32_e32 v74, v67, v77
	v_fmac_f32_e32 v74, v66, v76
	v_add_f32_e32 v74, v75, v74
	v_add_f32_e32 v78, 0, v74
	ds_read_b128 v[74:77], v70 offset:13312
	s_waitcnt lgkmcnt(0)
; #define LAS __attribute__((address_space(3)))
; __device__ __forceinline__ void ew_phase(const Frame& F, const bf16_t* f, const float* gpost, float alpha, const float* hin, float* hout, const float* gpre, bf16_t* xn, ...
;     ...
;                 for (int k = 0; k < 8; ++k)
; #pragma unroll
;                     for (int j = 0; j < 4; ++j) { const f32x4 w4 = *(const LAS f32x4*)(WF + k * DM + 256 * j + 4 * F.lane);
;                         a8[k] += (hv[j].x * w4.x + hv[j].y * w4.y) + (hv[j].z * w4.z + hv[j].w * w4.w); }
;                 const bool b5 = (F.lane & 32) != 0, b4 = (F.lane & 16) != 0, b3 = (F.lane & 8) != 0;
;                 float r4[4], r2v[2], r1;
; #pragma unroll
;                 for (int k = 0; k < 4; ++k) { const float keep = b5 ? a8[k + 4] : a8[k], give = b5 ? a8[k] : a8[k + 4]; r4[k] = keep + __shfl_xor(give, 32); }
; #pragma unroll
;                 for (int k = 0; k < 2; ++k) { const float keep = b4 ? r4[k + 2] : r4[k], give = b4 ? r4[k] : r4[k + 2]; r2v[k] = keep + __shfl_xor(give, 16); }
;                 { const float keep = b3 ? r2v[1] : r2v[0], give = b3 ? r2v[0] : r2v[1]; r1 = keep + __shfl_xor(give, 8); }
;                 r1 += __shfl_xor(r1, 4); r1 += __shfl_xor(r1, 2); r1 += __shfl_xor(r1, 1);
;                 if ((F.lane & 7) == 0) { const int k = (b5 ? 4 : 0) + (b4 ? 2 : 0) + (b3 ? 1 : 0); const float x = r1 + bfl[k];
	v_mul_f32_e32 v75, v63, v75
	v_fmac_f32_e32 v75, v62, v74
	v_mul_f32_e32 v74, v59, v77
	v_fmac_f32_e32 v74, v58, v76
	v_add_f32_e32 v74, v75, v74
	v_add_f32_e32 v78, v78, v74
	ds_read_b128 v[74:77], v70 offset:14336
	s_waitcnt lgkmcnt(0)
	v_mul_f32_e32 v75, v65, v75
	v_fmac_f32_e32 v75, v64, v74
	v_mul_f32_e32 v74, v61, v77
	v_fmac_f32_e32 v74, v60, v76
	v_add_f32_e32 v74, v75, v74
	v_add_f32_e32 v78, v78, v74
	ds_read_b128 v[74:77], v70 offset:15360
	s_waitcnt lgkmcnt(0)
	v_mul_f32_e32 v75, v57, v75
	v_fmac_f32_e32 v75, v56, v74
	v_mul_f32_e32 v74, v55, v77
	v_fmac_f32_e32 v74, v54, v76
	v_add_f32_e32 v74, v75, v74
	v_add_f32_e32 v74, v78, v74
	ds_read_b128 v[76:79], v70 offset:16384
	s_waitcnt lgkmcnt(0)
	v_mul_f32_e32 v75, v69, v77
	v_fmac_f32_e32 v75, v68, v76
	v_mul_f32_e32 v76, v67, v79
	v_fmac_f32_e32 v76, v66, v78
	v_add_f32_e32 v75, v75, v76
	ds_read_b128 v[76:79], v70 offset:17408
	v_add_f32_e32 v75, 0, v75
	s_waitcnt lgkmcnt(0)
	v_mul_f32_e32 v77, v63, v77
	v_fmac_f32_e32 v77, v62, v76
	v_mul_f32_e32 v76, v59, v79
	v_fmac_f32_e32 v76, v58, v78
	v_add_f32_e32 v76, v77, v76
	v_add_f32_e32 v75, v75, v76
	ds_read_b128 v[76:79], v70 offset:18432
	s_waitcnt lgkmcnt(0)
	v_mul_f32_e32 v77, v65, v77
	v_fmac_f32_e32 v77, v64, v76
	v_mul_f32_e32 v76, v61, v79
	v_fmac_f32_e32 v76, v60, v78
	v_add_f32_e32 v76, v77, v76
	v_add_f32_e32 v75, v75, v76
	ds_read_b128 v[76:79], v70 offset:19456
	s_waitcnt lgkmcnt(0)
	v_mul_f32_e32 v77, v57, v77
	v_fmac_f32_e32 v77, v56, v76
	v_mul_f32_e32 v76, v55, v79
	v_fmac_f32_e32 v76, v54, v78
	v_add_f32_e32 v76, v77, v76
	v_add_f32_e32 v75, v75, v76
	ds_read_b128 v[76:79], v70 offset:20480
	s_waitcnt lgkmcnt(0)
	v_mul_f32_e32 v77, v69, v77
	v_fmac_f32_e32 v77, v68, v76
	v_mul_f32_e32 v76, v67, v79
	v_fmac_f32_e32 v76, v66, v78
	v_add_f32_e32 v76, v77, v76
	v_add_f32_e32 v80, 0, v76
	ds_read_b128 v[76:79], v70 offset:21504
	s_waitcnt lgkmcnt(0)
	v_mul_f32_e32 v77, v63, v77
	v_fmac_f32_e32 v77, v62, v76
	v_mul_f32_e32 v76, v59, v79
	v_fmac_f32_e32 v76, v58, v78
	v_add_f32_e32 v76, v77, v76
	v_add_f32_e32 v80, v80, v76
	ds_read_b128 v[76:79], v70 offset:22528
	s_waitcnt lgkmcnt(0)
	v_mul_f32_e32 v77, v65, v77
	v_fmac_f32_e32 v77, v64, v76
	v_mul_f32_e32 v76, v61, v79
	v_fmac_f32_e32 v76, v60, v78
	v_add_f32_e32 v76, v77, v76
	v_add_f32_e32 v80, v80, v76
	ds_read_b128 v[76:79], v70 offset:23552
	s_waitcnt lgkmcnt(0)
	v_mul_f32_e32 v77, v57, v77
	v_fmac_f32_e32 v77, v56, v76
	v_mul_f32_e32 v76, v55, v79
	v_fmac_f32_e32 v76, v54, v78
	v_add_f32_e32 v76, v77, v76
	v_add_f32_e32 v80, v80, v76
	ds_read_b128 v[76:79], v70 offset:24576
	s_waitcnt lgkmcnt(0)
	v_mul_f32_e32 v77, v69, v77
	v_fmac_f32_e32 v77, v68, v76
	v_mul_f32_e32 v76, v67, v79
	v_fmac_f32_e32 v76, v66, v78
	v_add_f32_e32 v76, v77, v76
	v_add_f32_e32 v81, 0, v76
	ds_read_b128 v[76:79], v70 offset:25600
	s_waitcnt lgkmcnt(0)
	v_mul_f32_e32 v77, v63, v77
	v_fmac_f32_e32 v77, v62, v76
	v_mul_f32_e32 v76, v59, v79
	v_fmac_f32_e32 v76, v58, v78
	v_add_f32_e32 v76, v77, v76
	v_add_f32_e32 v81, v81, v76
	ds_read_b128 v[76:79], v70 offset:26624
	s_waitcnt lgkmcnt(0)
	v_mul_f32_e32 v77, v65, v77
	v_fmac_f32_e32 v77, v64, v76
	v_mul_f32_e32 v76, v61, v79
	v_fmac_f32_e32 v76, v60, v78
	v_add_f32_e32 v76, v77, v76
	v_add_f32_e32 v81, v81, v76
	ds_read_b128 v[76:79], v70 offset:27648
	s_waitcnt lgkmcnt(0)
	v_mul_f32_e32 v77, v57, v77
	v_fmac_f32_e32 v77, v56, v76
	v_mul_f32_e32 v76, v55, v79
	v_fmac_f32_e32 v76, v54, v78
	v_add_f32_e32 v76, v77, v76
	v_add_f32_e32 v81, v81, v76
	ds_read_b128 v[76:79], v70 offset:28672
	s_waitcnt lgkmcnt(0)
	v_mul_f32_e32 v69, v69, v77
	v_mul_f32_e32 v67, v67, v79
	v_fmac_f32_e32 v69, v68, v76
	v_fmac_f32_e32 v67, v66, v78
	v_add_f32_e32 v66, v69, v67
	v_add_f32_e32 v76, 0, v66
	ds_read_b128 v[66:69], v70 offset:29696
	s_waitcnt lgkmcnt(0)
	v_mul_f32_e32 v63, v63, v67
	v_mul_f32_e32 v59, v59, v69
	v_fmac_f32_e32 v63, v62, v66
	v_fmac_f32_e32 v59, v58, v68
	ds_read_b128 v[66:69], v70 offset:30720
	v_add_f32_e32 v58, v63, v59
	v_add_f32_e32 v58, v76, v58
	s_waitcnt lgkmcnt(0)
	v_mul_f32_e32 v59, v65, v67
	v_mul_f32_e32 v61, v61, v69
	v_fmac_f32_e32 v59, v64, v66
	v_fmac_f32_e32 v61, v60, v68
	v_add_f32_e32 v59, v59, v61
	v_add_f32_e32 v62, v58, v59
	ds_read_b128 v[58:61], v70 offset:31744
	s_waitcnt lgkmcnt(0)
	v_mul_f32_e32 v57, v57, v59
	v_mul_f32_e32 v55, v55, v61
	v_fmac_f32_e32 v57, v56, v58
	v_fmac_f32_e32 v55, v54, v60
	v_cndmask_b32_e64 v56, v71, v75, s[36:37]
	v_add_f32_e32 v54, v57, v55
	ds_bpermute_b32 v56, v100, v56
	v_cndmask_b32_e64 v57, v72, v80, s[36:37]
	ds_bpermute_b32 v57, v100, v57
	v_cndmask_b32_e64 v58, v73, v81, s[36:37]
	ds_bpermute_b32 v58, v100, v58
	v_cndmask_b32_e64 v55, v75, v71, s[36:37]
	s_waitcnt lgkmcnt(2)
	v_add_f32_e32 v55, v55, v56
	v_cndmask_b32_e64 v56, v80, v72, s[36:37]
	v_add_f32_e32 v54, v62, v54
	s_waitcnt lgkmcnt(1)
	v_add_f32_e32 v56, v56, v57
	v_cndmask_b32_e64 v57, v81, v73, s[36:37]
	s_waitcnt lgkmcnt(0)
	v_add_f32_e32 v57, v57, v58
	v_cndmask_b32_e64 v58, v54, v74, s[36:37]
	v_cndmask_b32_e64 v54, v74, v54, s[36:37]
	ds_bpermute_b32 v54, v100, v54
	s_waitcnt lgkmcnt(0)
	v_add_f32_e32 v54, v58, v54
	v_cndmask_b32_e64 v58, v57, v55, s[38:39]
	v_cndmask_b32_e64 v55, v55, v57, s[38:39]
	v_cndmask_b32_e64 v57, v54, v56, s[38:39]
	v_cndmask_b32_e64 v54, v56, v54, s[38:39]
	ds_bpermute_b32 v55, v99, v55
	ds_bpermute_b32 v54, v99, v54
	s_waitcnt lgkmcnt(1)
	v_add_f32_e32 v55, v58, v55
	s_waitcnt lgkmcnt(0)
	v_add_f32_e32 v54, v57, v54
	v_cndmask_b32_e64 v56, v54, v55, s[40:41]
	v_cndmask_b32_e64 v54, v55, v54, s[40:41]
	ds_bpermute_b32 v54, v97, v54
	s_waitcnt lgkmcnt(0)
	v_add_f32_e32 v54, v56, v54
	ds_bpermute_b32 v55, v96, v54
	s_waitcnt lgkmcnt(0)
	v_add_f32_e32 v54, v54, v55
	ds_bpermute_b32 v55, v90, v54
	s_waitcnt lgkmcnt(0)
	v_add_f32_e32 v54, v54, v55
	ds_bpermute_b32 v0, v0, v54
	s_and_saveexec_b64 s[0:1], s[42:43]
	s_cbranch_execz .LBB0_207
; __device__ __forceinline__ void ew_phase(const Frame& F, const bf16_t* f, const float* gpost, float alpha, const float* hin, float* hout, const float* gpre, bf16_t* xn, ...
;     ...
;                 if ((F.lane & 7) == 0) { const int k = (b5 ? 4 : 0) + (b4 ? 2 : 0) + (b3 ? 1 : 0); const float x = r1 + bfl[k];
;                     const float ls = fminf(x, 0.f) - log1pf(expf(-fabsf(x))); logf[(size_t)k * T + m] = ls * LOG2E; logf[(size_t)T * 8 + (size_t)k * T + m] = 0.f; }
	global_load_dword v55, v[48:49], off
	s_waitcnt lgkmcnt(0)
	v_add_f32_e32 v0, v54, v0
	s_lshl_b64 s[2:3], s[10:11], 2
	s_waitcnt vmcnt(0)
	v_add_f32_e32 v0, v0, v55
	v_mul_f32_e64 v54, |v0|, s27
	v_fma_f32 v55, |v0|, s27, -v54
	v_rndne_f32_e32 v56, v54
	v_fma_f32 v55, |v0|, s35, v55
	v_sub_f32_e32 v54, v54, v56
	v_add_f32_e32 v54, v54, v55
	v_cvt_i32_f32_e32 v58, v56
	v_exp_f32_e32 v59, v54
	v_lshl_add_u64 v[54:55], v[50:51], 0, s[2:3]
	v_lshl_add_u64 v[56:57], v[52:53], 0, s[2:3]
	s_mov_b32 s2, 0x42ce8ed0
	v_ldexp_f32 v58, v59, v58
	v_cmp_ngt_f32_e64 vcc, |v0|, s2
	s_mov_b32 s2, 0xc2b17218
	v_min_f32_e32 v60, 0, v0
	v_cndmask_b32_e32 v58, 0, v58, vcc
	v_cmp_nlt_f32_e64 vcc, |v0|, s2
	s_mov_b32 s2, 0x3f2aaaab
	s_nop 0
	v_cndmask_b32_e32 v0, v107, v58, vcc
	v_add_f32_e32 v61, 1.0, v0
	v_add_f32_e32 v62, -1.0, v61
	v_frexp_mant_f32_e32 v63, v61
	v_cvt_f64_f32_e32 v[58:59], v61
	v_sub_f32_e32 v64, v62, v61
	v_frexp_exp_i32_f64_e32 v58, v[58:59]
	v_cmp_gt_f32_e32 vcc, s2, v63
	v_sub_f32_e32 v62, v0, v62
	v_add_f32_e32 v59, 1.0, v64
	v_subbrev_co_u32_e32 v58, vcc, 0, v58, vcc
	v_add_f32_e32 v59, v62, v59
	v_sub_u32_e32 v62, 0, v58
	v_cvt_f32_i32_e32 v58, v58
	v_ldexp_f32 v61, v61, v62
	v_ldexp_f32 v59, v59, v62
	v_add_f32_e32 v62, -1.0, v61
	v_add_f32_e32 v63, 1.0, v61
	v_add_f32_e32 v64, 1.0, v62
	v_add_f32_e32 v65, -1.0, v63
	v_sub_f32_e32 v64, v61, v64
	v_sub_f32_e32 v61, v61, v65
	v_mul_f32_e32 v65, 0x3f317218, v58
	v_add_f32_e32 v64, v59, v64
	v_add_f32_e32 v59, v59, v61
	s_mov_b32 s2, 0x3f317218
	v_fma_f32 v61, v58, s2, -v65
	v_add_f32_e32 v66, v62, v64
	v_add_f32_e32 v67, v63, v59
	v_fmac_f32_e32 v61, 0xb102e308, v58
	v_sub_f32_e32 v58, v62, v66
	v_sub_f32_e32 v62, v63, v67
	v_rcp_f32_e32 v63, v67
	v_add_f32_e32 v68, v65, v61
	v_add_f32_e32 v59, v59, v62
	v_sub_f32_e32 v62, v68, v65
	v_sub_f32_e32 v61, v61, v62
	v_mul_f32_e32 v62, v66, v63
	v_add_f32_e32 v58, v64, v58
	v_mul_f32_e32 v64, v67, v62
	v_fma_f32 v65, v62, v67, -v64
	v_fmac_f32_e32 v65, v62, v59
	v_add_f32_e32 v69, v64, v65
	v_sub_f32_e32 v70, v66, v69
	v_sub_f32_e32 v64, v69, v64
	v_sub_f32_e32 v66, v66, v70
	v_sub_f32_e32 v64, v64, v65
	v_sub_f32_e32 v65, v66, v69
	v_add_f32_e32 v58, v58, v65
	v_add_f32_e32 v58, v64, v58
	v_add_f32_e32 v64, v70, v58
	v_mul_f32_e32 v65, v63, v64
	v_sub_f32_e32 v66, v70, v64
	v_mul_f32_e32 v69, v67, v65
	v_add_f32_e32 v58, v58, v66
	v_add_f32_e32 v66, v62, v65
	v_fma_f32 v67, v65, v67, -v69
	v_sub_f32_e32 v62, v66, v62
	v_fmac_f32_e32 v67, v65, v59
	v_sub_f32_e32 v59, v65, v62
	v_add_f32_e32 v62, v69, v67
	v_sub_f32_e32 v65, v62, v69
	v_sub_f32_e32 v69, v64, v62
	v_sub_f32_e32 v64, v64, v69
	v_sub_f32_e32 v62, v64, v62
	v_sub_f32_e32 v65, v65, v67
	v_add_f32_e32 v58, v58, v62
	v_add_f32_e32 v58, v65, v58
	v_add_f32_e32 v58, v69, v58
	v_mul_f32_e32 v58, v63, v58
	v_add_f32_e32 v58, v59, v58
	v_add_f32_e32 v59, v66, v58
	v_mul_f32_e32 v62, v59, v59
	v_fmamk_f32 v65, v62, 0x3e9b6dac, v235
	v_sub_f32_e32 v63, v59, v66
	v_ldexp_f32 v64, v59, 1
	v_mul_f32_e32 v59, v59, v62
	v_fmaak_f32 v62, v62, v65, 0x3f2aaada
	v_mul_f32_e32 v59, v59, v62
	v_add_f32_e32 v62, v64, v59
	v_sub_f32_e32 v58, v58, v63
	v_sub_f32_e32 v63, v62, v64
	v_ldexp_f32 v58, v58, 1
	v_sub_f32_e32 v59, v59, v63
	v_add_f32_e32 v58, v58, v59
	v_add_f32_e32 v59, v62, v58
	v_sub_f32_e32 v62, v59, v62
	v_add_f32_e32 v63, v68, v59
	v_sub_f32_e32 v58, v58, v62
	v_sub_f32_e32 v62, v63, v68
	v_sub_f32_e32 v64, v63, v62
	v_sub_f32_e32 v59, v59, v62
	v_add_f32_e32 v62, v61, v58
	v_sub_f32_e32 v64, v68, v64
	v_sub_f32_e32 v65, v62, v61
	v_add_f32_e32 v59, v59, v64
	v_sub_f32_e32 v64, v62, v65
	v_sub_f32_e32 v58, v58, v65
	v_sub_f32_e32 v61, v61, v64
	v_add_f32_e32 v59, v62, v59
	v_add_f32_e32 v58, v58, v61
	v_add_f32_e32 v61, v63, v59
	v_sub_f32_e32 v62, v61, v63
	v_sub_f32_e32 v59, v59, v62
	v_add_f32_e32 v58, v58, v59
	s_mov_b32 s2, 0x7f800000
	v_add_f32_e32 v58, v61, v58
	v_cmp_neq_f32_e32 vcc, s2, v0
	s_mov_b32 s2, 0x33800000
	s_nop 0
	v_cndmask_b32_e32 v58, v107, v58, vcc
	v_cmp_lt_f32_e64 vcc, |v0|, s2
	s_nop 1
	v_cndmask_b32_e32 v0, v58, v0, vcc
	v_sub_f32_e32 v0, v60, v0
	v_mul_f32_e32 v0, 0x3fb8aa3b, v0
	global_store_dword v[54:55], v0, off
	global_store_dword v[56:57], v1, off
	s_branch .LBB0_207

; __device__ __forceinline__ float bf_lo(unsigned w) { return __uint_as_float(w << 16); }
; __device__ __forceinline__ float bf_hi(unsigned w) { return __uint_as_float(w & 0xffff0000u); }
; __device__ __forceinline__ float wave_sum(float v) {
; #pragma unroll
;     for (int o = 1; o < 64; o <<= 1) v += __shfl_xor(v, o);
;     return v;
; __device__ __forceinline__ void ew_phase(const Frame& F, const bf16_t* f, const float* gpost, float alpha, const float* hin, float* hout, const float* gpre, bf16_t* xn, ...
;     ...
;     for (int it_ = 0; it_ < it_n; ++it_) {
;         const int m = prow0 >= 0 ? prow0 + F.wave * 8 + it_ : F.gw + it_ * F.NGW; if (m >= T) break;
;         const u32x2* fr = (const u32x2*)(f + (size_t)m * DM) + F.lane; const f32x4* hr = (const f32x4*)(hin + (size_t)m * DM) + F.lane;
;         f32x4 fv[4], hv[4]; float s = 0.f;
; #pragma unroll
;         for (int j = 0; j < 4; ++j) { const u32x2 w = fr[64 * j]; hv[j] = in24 ? load24(h24 + (size_t)m * (DM * 3), F.lane + 64 * j) : hr[64 * j]; fv[j] = (f32x4){bf_lo(w.x), bf_hi(w.x), bf_lo(w.y), bf_hi(w.y)};
;             s += (fv[j].x * fv[j].x + fv[j].y * fv[j].y) + (fv[j].z * fv[j].z + fv[j].w * fv[j].w); }
;         const float rstd = alpha / sqrtf(wave_sum(s) * (1.f / DM) + RMS_EPS);
.LBB0_812:
	v_readlane_b32 s0, v252, 11
	s_add_i32 s8, s2, s3
	v_readlane_b32 s1, v252, 12
	s_and_b64 s[0:1], s[0:1], exec
	s_cselect_b32 s8, s8, s12
	s_cmpk_gt_i32 s8, 0x3fff
	s_mov_b64 s[0:1], -1
	s_cbranch_scc1 .LBB0_811
	s_ashr_i32 s9, s8, 31
	s_lshl_b64 s[0:1], s[8:9], 11
	v_lshl_add_u64 v[78:79], v[36:37], 0, s[0:1]
	s_mul_i32 s0, s8, 0xc00
	s_mul_hi_i32 s1, s8, 0xc00
	s_add_u32 s0, s25, s0
	s_addc_u32 s1, s27, s1
	v_lshl_add_u64 v[48:49], s[0:1], 0, v[40:41]
	v_lshl_add_u64 v[162:163], s[0:1], 0, v[42:43]
	v_lshl_add_u64 v[164:165], s[0:1], 0, v[44:45]
	v_lshl_add_u64 v[166:167], s[0:1], 0, v[46:47]
	global_load_dwordx2 v[56:57], v[78:79], off
	global_load_dwordx2 v[52:53], v[48:49], off
	global_load_dwordx2 v[54:55], v[48:49], off offset:4
	global_load_dwordx2 v[64:65], v[78:79], off offset:512
	global_load_dwordx2 v[62:63], v[162:163], off
	global_load_dwordx2 v[66:67], v[162:163], off offset:4
	global_load_dwordx2 v[76:77], v[78:79], off offset:1024
	global_load_dwordx2 v[72:73], v[164:165], off
	global_load_dwordx2 v[74:75], v[164:165], off offset:4
	global_load_dwordx2 v[84:85], v[78:79], off offset:1536
	global_load_dwordx2 v[82:83], v[166:167], off
	global_load_dwordx2 v[86:87], v[166:167], off offset:4
	s_mov_b32 s14, 0xff00
	s_waitcnt vmcnt(10)
	v_lshrrev_b32_e32 v53, 8, v53
	s_waitcnt vmcnt(9)
	v_lshlrev_b32_e32 v51, 24, v55
	v_lshlrev_b32_e32 v54, 16, v54
	v_and_b32_e32 v53, 0xffff00, v53
	v_and_b32_sdwa v58, v52, s14 dst_sel:DWORD dst_unused:UNUSED_PAD src0_sel:WORD_1 src1_sel:DWORD
	v_lshlrev_b32_e32 v50, 8, v52
	v_or_b32_e32 v52, v51, v53
	v_or_b32_e32 v51, v54, v58
	v_and_b32_e32 v53, 0xffffff00, v55
	v_lshlrev_b32_e32 v54, 16, v56
	v_and_b32_e32 v55, 0xffff0000, v56
	v_lshlrev_b32_e32 v56, 16, v57
	v_and_b32_e32 v57, 0xffff0000, v57
	v_mul_f32_e32 v58, v57, v57
	v_pk_fma_f32 v[90:91], v[56:57], v[56:57], v[58:59] op_sel_hi:[1,1,0]
	v_lshl_add_u64 v[58:59], s[0:1], 0, v[42:43]
	v_mov_b32_e32 v98, v90
	s_waitcnt vmcnt(7)
	v_lshrrev_b32_e32 v63, 8, v63
	s_waitcnt vmcnt(6)
	v_lshlrev_b32_e32 v61, 24, v67
	v_lshlrev_b32_e32 v66, 16, v66
	v_and_b32_e32 v63, 0xffff00, v63
	v_and_b32_sdwa v68, v62, s14 dst_sel:DWORD dst_unused:UNUSED_PAD src0_sel:WORD_1 src1_sel:DWORD
	v_lshlrev_b32_e32 v60, 8, v62
	v_or_b32_e32 v62, v61, v63
	v_or_b32_e32 v61, v66, v68
	v_and_b32_e32 v63, 0xffffff00, v67
	v_lshlrev_b32_e32 v67, 16, v65
	v_lshlrev_b32_e32 v66, 16, v64
	v_and_b32_e32 v65, 0xffff0000, v65
	v_and_b32_e32 v64, 0xffff0000, v64
	v_pk_mul_f32 v[68:69], v[64:65], v[64:65]
	s_nop 0
	v_pk_fma_f32 v[94:95], v[66:67], v[66:67], v[68:69]
	v_lshl_add_u64 v[68:69], s[0:1], 0, v[44:45]
	v_lshl_add_u64 v[78:79], s[0:1], 0, v[46:47]
	v_pk_add_f32 v[94:95], v[94:95], v[94:95] op_sel:[0,1] op_sel_hi:[1,0]
	s_waitcnt vmcnt(4)
	v_lshrrev_b32_e32 v73, 8, v73
	s_waitcnt vmcnt(3)
	v_lshlrev_b32_e32 v71, 24, v75
	v_lshlrev_b32_e32 v74, 16, v74
	s_waitcnt vmcnt(1)
	v_lshrrev_b32_e32 v83, 8, v83
	v_and_b32_e32 v73, 0xffff00, v73
	v_and_b32_sdwa v80, v72, s14 dst_sel:DWORD dst_unused:UNUSED_PAD src0_sel:WORD_1 src1_sel:DWORD
	s_waitcnt vmcnt(0)
	v_lshlrev_b32_e32 v81, 24, v87
	v_lshlrev_b32_e32 v86, 16, v86
	v_and_b32_e32 v83, 0xffff00, v83
	v_and_b32_sdwa v88, v82, s14 dst_sel:DWORD dst_unused:UNUSED_PAD src0_sel:WORD_1 src1_sel:DWORD
	v_lshlrev_b32_e32 v70, 8, v72
	v_or_b32_e32 v72, v71, v73
	v_or_b32_e32 v71, v74, v80
	v_lshlrev_b32_e32 v80, 8, v82
	v_or_b32_e32 v82, v81, v83
	v_or_b32_e32 v81, v86, v88
	v_and_b32_e32 v83, 0xffffff00, v87
	v_and_b32_e32 v87, 0xffff0000, v84
	v_mul_f32_e32 v86, v55, v55
	v_lshlrev_b32_e32 v89, 16, v84
	v_pk_fma_f32 v[96:97], v[54:55], v[54:55], v[86:87] op_sel_hi:[1,1,0]
	v_mov_b32_e32 v99, v89
	v_mov_b32_e32 v88, v96
	v_and_b32_e32 v73, 0xffffff00, v75
	v_and_b32_e32 v75, 0xffff0000, v76
	v_mul_f32_e32 v93, v87, v87
	v_pk_add_f32 v[90:91], v[96:97], v[90:91]
	v_pk_mul_f32 v[96:97], v[88:89], v[98:99]
	v_lshlrev_b32_e32 v74, 16, v76
	v_lshlrev_b32_e32 v76, 16, v77
	v_and_b32_e32 v77, 0xffff0000, v77
	v_mov_b32_e32 v91, v97
	v_mov_b32_e32 v95, v93
	v_mul_f32_e32 v86, v75, v75
	v_lshlrev_b32_e32 v84, 16, v85
	v_and_b32_e32 v85, 0xffff0000, v85
	v_pk_add_f32 v[90:91], v[90:91], v[94:95]
	v_pk_fma_f32 v[94:95], v[74:75], v[74:75], v[86:87] op_sel_hi:[1,1,0]
	v_mul_f32_e32 v86, v77, v77
	v_mul_f32_e32 v100, v84, v84
	v_mul_f32_e32 v101, v85, v85
	v_pk_fma_f32 v[96:97], v[76:77], v[76:77], v[86:87] op_sel_hi:[1,1,0]
	v_mov_b32_e32 v95, v100
	v_mov_b32_e32 v97, v101
	v_pk_add_f32 v[94:95], v[94:95], v[96:97]
	v_and_b32_e32 v88, 64, v230
	v_pk_add_f32 v[90:91], v[90:91], v[94:95]
	v_add_u32_e32 v95, 64, v88
	v_add_f32_e32 v86, v90, v91
	s_mov_b32 s14, 0xf800000
	s_nop 1
	v_add_f32_dpp v86, v86, v86 quad_perm:[1,0,3,2] row_mask:0xf bank_mask:0xf
	s_nop 1
	v_add_f32_dpp v86, v86, v86 quad_perm:[2,3,0,1] row_mask:0xf bank_mask:0xf
	s_nop 1
	v_add_f32_dpp v86, v86, v86 row_half_mirror row_mask:0xf bank_mask:0xf
	s_nop 1
	v_add_f32_dpp v86, v86, v86 row_mirror row_mask:0xf bank_mask:0xf
	v_xor_b32_e32 v94, 16, v230
	v_cmp_lt_i32_e32 vcc, v94, v95
	s_nop 1
	v_cndmask_b32_e32 v94, v230, v94, vcc
	v_lshlrev_b32_e32 v94, 2, v94
	ds_bpermute_b32 v96, v94, v86
	s_waitcnt lgkmcnt(0)
	v_add_f32_e32 v86, v86, v96
	v_xor_b32_e32 v96, 32, v230
	v_cmp_lt_i32_e32 vcc, v96, v95
	s_nop 1
	v_cndmask_b32_e32 v95, v230, v96, vcc
	v_lshlrev_b32_e32 v95, 2, v95
	ds_bpermute_b32 v96, v95, v86
	s_waitcnt lgkmcnt(0)
; __device__ __forceinline__ void ew_phase(const Frame& F, const bf16_t* f, const float* gpost, float alpha, const float* hin, float* hout, const float* gpre, bf16_t* xn, ...
;     ...
;         const float rstd = alpha / sqrtf(wave_sum(s) * (1.f / DM) + RMS_EPS);
;         float s2 = 0.f; f32x4* ho = (f32x4*)(hout + (size_t)m * DM) + F.lane;
; #pragma unroll
;         for (int j = 0; j < 4; ++j) { hv[j] = hv[j] + fv[j] * rstd * gp[j]; if (out24) store24(h24 + (size_t)m * (DM * 3), F.lane + 64 * j, hv[j]); else ho[64 * j] = hv[j]; s2 += (hv[j].x * hv[j].x + hv[j].y * hv[j].y) + (hv[j].z * hv[j].z + hv[j].w * hv[j].w); }
;         if (gpre) {
	v_add_f32_e32 v86, v86, v96
	v_fmamk_f32 v86, v86, 0x3a800000, v225
	v_cmp_gt_f32_e32 vcc, s14, v86
	v_mul_f32_e32 v96, 0x4f800000, v86
	s_nop 0
	v_cndmask_b32_e32 v86, v86, v96, vcc
	v_sqrt_f32_e32 v96, v86
	s_nop 0
	v_add_u32_e32 v97, -1, v96
	v_fma_f32 v98, -v97, v96, v86
	v_cmp_ge_f32_e64 s[0:1], 0, v98
	v_add_u32_e32 v98, 1, v96
	s_nop 0
	v_cndmask_b32_e64 v97, v96, v97, s[0:1]
	v_fma_f32 v96, -v98, v96, v86
	v_cmp_lt_f32_e64 s[0:1], 0, v96
	s_nop 1
	v_cndmask_b32_e64 v96, v97, v98, s[0:1]
	v_mul_f32_e32 v97, 0x37800000, v96
	v_cndmask_b32_e32 v96, v96, v97, vcc
	v_cmp_class_f32_e32 vcc, v86, v226
	s_nop 1
	v_cndmask_b32_e32 v86, v96, v86, vcc
	v_div_scale_f32 v96, s[0:1], v86, v86, 1.0
	v_rcp_f32_e32 v97, v96
	s_mov_b32 s0, 0x7060503
	v_fma_f32 v98, -v96, v97, 1.0
	v_fmac_f32_e32 v97, v98, v97
	v_div_scale_f32 v98, vcc, 1.0, v86, 1.0
	v_mul_f32_e32 v99, v98, v97
	v_fma_f32 v100, -v96, v99, v98
	v_fmac_f32_e32 v99, v100, v97
	v_fma_f32 v96, -v96, v99, v98
	v_div_fmas_f32 v96, v96, v97, v99
	v_div_fixup_f32 v96, v96, v86, 1.0
	v_pk_mul_f32 v[54:55], v[96:97], v[54:55] op_sel_hi:[0,1]
	v_pk_mul_f32 v[56:57], v[96:97], v[56:57] op_sel_hi:[0,1]
	v_pk_fma_f32 v[52:53], v[4:5], v[56:57], v[52:53]
	v_pk_fma_f32 v[50:51], v[2:3], v[54:55], v[50:51]
	v_bfe_u32 v57, v52, 8, 1
	v_bfe_u32 v55, v51, 8, 1
	v_bfe_u32 v54, v50, 8, 1
	v_add3_u32 v55, v51, v55, s13
	v_add3_u32 v57, v52, v57, s13
	v_bfe_u32 v97, v53, 8, 1
	v_add3_u32 v54, v50, v54, s13
	v_lshrrev_b32_e32 v56, 8, v55
	v_lshrrev_b32_e32 v86, 8, v57
	v_add3_u32 v97, v53, v97, s13
	v_alignbit_b32 v54, v56, v54, 8
	v_alignbit_b32 v55, v86, v55, 16
	v_perm_b32 v56, v97, v57, s0
	global_store_dwordx3 v[48:49], v[54:56], off
	v_mov_b32_e32 v48, v66
	v_mov_b32_e32 v49, v64
	v_mov_b32_e32 v64, v67
	v_pk_mul_f32 v[54:55], v[96:97], v[48:49] op_sel_hi:[0,1]
	v_pk_mul_f32 v[48:49], v[96:97], v[64:65] op_sel_hi:[0,1]
	v_pk_fma_f32 v[48:49], v[16:17], v[48:49], v[62:63]
	v_pk_fma_f32 v[54:55], v[14:15], v[54:55], v[60:61]
	v_bfe_u32 v61, v48, 8, 1
	v_bfe_u32 v57, v55, 8, 1
	v_bfe_u32 v56, v54, 8, 1
	v_add3_u32 v57, v55, v57, s13
	v_add3_u32 v62, v48, v61, s13
	v_bfe_u32 v63, v49, 8, 1
	v_add3_u32 v56, v54, v56, s13
	v_lshrrev_b32_e32 v60, 8, v57
	v_lshrrev_b32_e32 v61, 8, v62
	v_add3_u32 v63, v49, v63, s13
	v_alignbit_b32 v60, v60, v56, 8
	v_alignbit_b32 v61, v61, v57, 16
	v_perm_b32 v62, v63, v62, s0
	global_store_dwordx3 v[58:59], v[60:62], off
	v_pk_mul_f32 v[58:59], v[96:97], v[74:75] op_sel_hi:[0,1]
	v_pk_mul_f32 v[56:57], v[96:97], v[76:77] op_sel_hi:[0,1]
	v_pk_fma_f32 v[56:57], v[20:21], v[56:57], v[72:73]
	v_pk_fma_f32 v[58:59], v[18:19], v[58:59], v[70:71]
	v_bfe_u32 v63, v56, 8, 1
	v_bfe_u32 v61, v59, 8, 1
	v_bfe_u32 v60, v58, 8, 1
	v_add3_u32 v61, v59, v61, s13
	v_add3_u32 v63, v56, v63, s13
	v_bfe_u32 v65, v57, 8, 1
	v_add3_u32 v60, v58, v60, s13
	v_lshrrev_b32_e32 v62, 8, v61
	v_lshrrev_b32_e32 v64, 8, v63
	v_add3_u32 v65, v57, v65, s13
	v_alignbit_b32 v60, v62, v60, 8
	v_alignbit_b32 v61, v64, v61, 16
	v_perm_b32 v62, v65, v63, s0
	v_mov_b32_e32 v86, v89
	global_store_dwordx3 v[68:69], v[60:62], off
	s_and_b64 vcc, exec, s[40:41]
	s_nop 0
	v_pk_mul_f32 v[62:63], v[86:87], v[96:97] op_sel_hi:[1,0]
	v_pk_mul_f32 v[60:61], v[84:85], v[96:97] op_sel_hi:[1,0]
	v_pk_fma_f32 v[62:63], v[30:31], v[62:63], v[80:81]
	v_pk_fma_f32 v[60:61], v[32:33], v[60:61], v[82:83]
	v_bfe_u32 v65, v63, 8, 1
	v_bfe_u32 v67, v60, 8, 1
	v_bfe_u32 v64, v62, 8, 1
	v_add3_u32 v65, v63, v65, s13
	v_add3_u32 v67, v60, v67, s13
	v_bfe_u32 v69, v61, 8, 1
	v_add3_u32 v64, v62, v64, s13
	v_lshrrev_b32_e32 v66, 8, v65
	v_lshrrev_b32_e32 v68, 8, v67
	v_add3_u32 v69, v61, v69, s13
	v_alignbit_b32 v64, v66, v64, 8
	v_alignbit_b32 v65, v68, v65, 16
	v_perm_b32 v66, v69, v67, s0
	global_store_dwordx3 v[78:79], v[64:66], off
	s_cbranch_vccnz .LBB0_810
; __device__ __forceinline__ unsigned cvt_pk_bf16(float lo, float hi) { f32x2 v = {lo, hi}; bf16x2_t b = __builtin_convertvector(v, bf16x2_t); return __builtin_bit_cast(unsigned, b); }
; __device__ __forceinline__ void ew_phase(const Frame& F, const bf16_t* f, const float* gpost, float alpha, const float* hin, float* hout, const float* gpre, bf16_t* xn, ...
;     ...
;         if (gpre) {
;             const float r2 = 1.0f / sqrtf(wave_sum(s2) * (1.f / DM) + RMS_EPS);
;             u32x2* o8 = (u32x2*)(xn + (size_t)m * DM) + F.lane;
; #pragma unroll
;             for (int j = 0; j < 4; ++j) { hv[j] = hv[j] * r2 * gq[j]; u32x2 w; w.x = cvt_pk_bf16(hv[j].x, hv[j].y); w.y = cvt_pk_bf16(hv[j].z, hv[j].w); o8[64 * j] = w; }
	s_nop 0
	v_pk_mul_f32 v[64:65], v[52:53], v[52:53]
	v_pk_mul_f32 v[66:67], v[50:51], v[50:51]
	v_mov_b32_e32 v69, v65
	v_mov_b32_e32 v68, v66
	v_pk_mov_b32 v[64:65], v[66:67], v[64:65] op_sel:[1,0]
	v_pk_mul_f32 v[66:67], v[48:49], v[48:49]
	v_pk_add_f32 v[64:65], v[68:69], v[64:65]
	v_pk_mul_f32 v[68:69], v[54:55], v[54:55]
	v_pk_add_f32 v[64:65], v[64:65], v[64:65] op_sel_hi:[0,1]
	v_mov_b32_e32 v70, v68
	v_mov_b32_e32 v71, v67
	v_pk_mov_b32 v[66:67], v[68:69], v[66:67] op_sel:[1,0]
	v_mul_f32_e32 v64, v58, v58
	v_pk_add_f32 v[66:67], v[70:71], v[66:67]
	v_pk_fma_f32 v[68:69], v[58:59], v[58:59], v[64:65] op_sel_hi:[1,1,0]
	v_mul_f32_e32 v64, v56, v56
	v_pk_add_f32 v[66:67], v[66:67], v[66:67] op_sel_hi:[0,1]
	v_pk_fma_f32 v[70:71], v[56:57], v[56:57], v[64:65] op_sel_hi:[1,1,0]
	v_mul_f32_e32 v68, v62, v62
	v_mul_f32_e32 v70, v63, v63
	v_mul_f32_e32 v64, v61, v61
	v_mul_f32_e32 v66, v60, v60
	v_pk_add_f32 v[68:69], v[68:69], v[70:71]
	v_pk_add_f32 v[64:65], v[64:65], v[66:67]
	s_lshl_b64 s[8:9], s[8:9], 10
	v_pk_add_f32 v[64:65], v[68:69], v[64:65]
	s_nop 0
	v_add_f32_e32 v64, v64, v65
	s_nop 1
	v_add_f32_dpp v64, v64, v64 quad_perm:[1,0,3,2] row_mask:0xf bank_mask:0xf
	s_nop 1
	v_add_f32_dpp v64, v64, v64 quad_perm:[2,3,0,1] row_mask:0xf bank_mask:0xf
	s_nop 1
	v_add_f32_dpp v64, v64, v64 row_half_mirror row_mask:0xf bank_mask:0xf
	s_nop 1
	v_add_f32_dpp v64, v64, v64 row_mirror row_mask:0xf bank_mask:0xf
	ds_bpermute_b32 v65, v94, v64
	s_waitcnt lgkmcnt(0)
	v_add_f32_e32 v64, v64, v65
	ds_bpermute_b32 v65, v95, v64
	s_waitcnt lgkmcnt(0)
	v_add_f32_e32 v64, v64, v65
	v_fmamk_f32 v64, v64, 0x3a800000, v225
	v_mul_f32_e32 v65, 0x4f800000, v64
	v_cmp_gt_f32_e32 vcc, s14, v64
	s_nop 1
	v_cndmask_b32_e32 v64, v64, v65, vcc
	v_sqrt_f32_e32 v65, v64
	s_nop 0
	v_add_u32_e32 v66, -1, v65
	v_add_u32_e32 v67, 1, v65
	v_fma_f32 v68, -v66, v65, v64
	v_fma_f32 v69, -v67, v65, v64
	v_cmp_ge_f32_e64 s[0:1], 0, v68
	s_nop 1
	v_cndmask_b32_e64 v65, v65, v66, s[0:1]
	v_cmp_lt_f32_e64 s[0:1], 0, v69
	s_nop 1
	v_cndmask_b32_e64 v65, v65, v67, s[0:1]
	v_mul_f32_e32 v66, 0x37800000, v65
	v_cndmask_b32_e32 v65, v65, v66, vcc
	v_cmp_class_f32_e32 vcc, v64, v226
	s_nop 1
	v_cndmask_b32_e32 v66, v65, v64, vcc
	v_div_scale_f32 v67, s[0:1], v66, v66, 1.0
	v_rcp_f32_e32 v68, v67
	v_div_scale_f32 v69, vcc, 1.0, v66, 1.0
	v_lshl_add_u64 v[64:65], s[8:9], 1, v[38:39]
	v_fma_f32 v70, -v67, v68, 1.0
	v_fmac_f32_e32 v68, v70, v68
	v_mul_f32_e32 v70, v69, v68
	v_fma_f32 v71, -v67, v70, v69
	v_fmac_f32_e32 v70, v71, v68
	v_fma_f32 v67, -v67, v70, v69
	v_div_fmas_f32 v67, v67, v68, v70
	v_div_fixup_f32 v66, v67, v66, 1.0
	v_pk_mul_f32 v[50:51], v[50:51], v[66:67] op_sel_hi:[1,0]
	v_pk_mul_f32 v[52:53], v[52:53], v[66:67] op_sel_hi:[1,0]
	v_pk_mul_f32 v[50:51], v[10:11], v[50:51]
	v_pk_mul_f32 v[52:53], v[12:13], v[52:53]
	v_cvt_pk_bf16_f32 v50, v50, v51
	v_cvt_pk_bf16_f32 v51, v52, v53
	global_store_dwordx2 v[64:65], v[50:51], off
	v_pk_mul_f32 v[50:51], v[54:55], v[66:67] op_sel_hi:[1,0]
	v_pk_mul_f32 v[48:49], v[48:49], v[66:67] op_sel_hi:[1,0]
	v_pk_mul_f32 v[50:51], v[6:7], v[50:51]
	v_pk_mul_f32 v[48:49], v[8:9], v[48:49]
	v_cvt_pk_bf16_f32 v50, v50, v51
	v_cvt_pk_bf16_f32 v51, v48, v49
	global_store_dwordx2 v[64:65], v[50:51], off offset:512
	v_pk_mul_f32 v[48:49], v[58:59], v[66:67] op_sel_hi:[1,0]
	v_pk_mul_f32 v[50:51], v[56:57], v[66:67] op_sel_hi:[1,0]
	v_pk_mul_f32 v[48:49], v[26:27], v[48:49]
	v_pk_mul_f32 v[50:51], v[28:29], v[50:51]
	v_cvt_pk_bf16_f32 v48, v48, v49
	v_cvt_pk_bf16_f32 v49, v50, v51
	global_store_dwordx2 v[64:65], v[48:49], off offset:1024
	v_pk_mul_f32 v[48:49], v[62:63], v[66:67] op_sel_hi:[1,0]
	v_pk_mul_f32 v[50:51], v[60:61], v[66:67] op_sel_hi:[1,0]
	v_pk_mul_f32 v[48:49], v[22:23], v[48:49]
	v_pk_mul_f32 v[50:51], v[24:25], v[50:51]
	v_cvt_pk_bf16_f32 v48, v48, v49
	v_cvt_pk_bf16_f32 v49, v50, v51
	global_store_dwordx2 v[64:65], v[48:49], off offset:1536
	s_branch .LBB0_810

; __device__ __forceinline__ float bf_lo(unsigned w) { return __uint_as_float(w << 16); }
; __device__ __forceinline__ float bf_hi(unsigned w) { return __uint_as_float(w & 0xffff0000u); }
; __device__ __forceinline__ float wave_sum(float v) {
; #pragma unroll
;     for (int o = 1; o < 64; o <<= 1) v += __shfl_xor(v, o);
;     return v;
; __device__ __forceinline__ void ew_phase(const Frame& F, const bf16_t* f, const float* gpost, float alpha, const float* hin, float* hout, const float* gpre, bf16_t* xn, ...
;     ...
;     for (int it_ = 0; it_ < it_n; ++it_) {
;         const int m = prow0 >= 0 ? prow0 + F.wave * 8 + it_ : F.gw + it_ * F.NGW; if (m >= T) break;
;         const u32x2* fr = (const u32x2*)(f + (size_t)m * DM) + F.lane; const f32x4* hr = (const f32x4*)(hin + (size_t)m * DM) + F.lane;
;         f32x4 fv[4], hv[4]; float s = 0.f;
; #pragma unroll
;         for (int j = 0; j < 4; ++j) { const u32x2 w = fr[64 * j]; hv[j] = in24 ? load24(h24 + (size_t)m * (DM * 3), F.lane + 64 * j) : hr[64 * j]; fv[j] = (f32x4){bf_lo(w.x), bf_hi(w.x), bf_lo(w.y), bf_hi(w.y)};
;             s += (fv[j].x * fv[j].x + fv[j].y * fv[j].y) + (fv[j].z * fv[j].z + fv[j].w * fv[j].w); }
;         const float rstd = alpha / sqrtf(wave_sum(s) * (1.f / DM) + RMS_EPS);
.LBB0_905:
	v_readlane_b32 s0, v252, 11
	s_add_i32 s6, s2, s3
	v_readlane_b32 s1, v252, 12
	s_and_b64 s[0:1], s[0:1], exec
	s_cselect_b32 s8, s6, s12
	s_cmpk_gt_i32 s8, 0x3fff
	s_mov_b64 s[0:1], -1
	s_cbranch_scc1 .LBB0_904
	s_ashr_i32 s9, s8, 31
	s_lshl_b64 s[6:7], s[8:9], 11
	s_mul_i32 s0, s8, 0xc00
	s_mul_hi_i32 s1, s8, 0xc00
	s_add_u32 s0, s13, s0
	s_addc_u32 s1, s14, s1
	v_lshl_add_u64 v[68:69], v[44:45], 0, s[6:7]
	v_lshl_add_u64 v[48:49], s[0:1], 0, v[36:37]
	v_lshl_add_u64 v[58:59], s[0:1], 0, v[38:39]
	v_lshl_add_u64 v[162:163], s[0:1], 0, v[40:41]
	v_lshl_add_u64 v[164:165], s[0:1], 0, v[42:43]
	global_load_dwordx2 v[56:57], v[68:69], off
	global_load_dwordx2 v[52:53], v[48:49], off
	global_load_dwordx2 v[54:55], v[48:49], off offset:4
	global_load_dwordx2 v[64:65], v[68:69], off offset:512
	global_load_dwordx2 v[62:63], v[58:59], off
	global_load_dwordx2 v[66:67], v[58:59], off offset:4
	global_load_dwordx2 v[72:73], v[68:69], off offset:1024
	global_load_dwordx2 v[76:77], v[162:163], off
	global_load_dwordx2 v[78:79], v[162:163], off offset:4
	global_load_dwordx2 v[80:81], v[68:69], off offset:1536
	global_load_dwordx2 v[166:167], v[164:165], off
	global_load_dwordx2 v[82:83], v[164:165], off offset:4
	s_mov_b32 s8, 0xff00
	s_add_i32 s3, s3, 1
	s_addk_i32 s12, 0x800
	s_cmp_eq_u32 s3, 8
	s_waitcnt vmcnt(10)
	v_lshrrev_b32_e32 v51, 8, v53
	s_waitcnt vmcnt(9)
	v_lshlrev_b32_e32 v0, 24, v55
	v_lshlrev_b32_e32 v35, 16, v54
	v_and_b32_e32 v51, 0xffff00, v51
	v_and_b32_sdwa v53, v52, s8 dst_sel:DWORD dst_unused:UNUSED_PAD src0_sel:WORD_1 src1_sel:DWORD
	v_lshlrev_b32_e32 v50, 8, v52
	v_or_b32_e32 v52, v0, v51
	v_or_b32_e32 v51, v35, v53
	v_and_b32_e32 v53, 0xffffff00, v55
	v_lshlrev_b32_e32 v54, 16, v56
	v_and_b32_e32 v55, 0xffff0000, v56
	v_lshlrev_b32_e32 v56, 16, v57
	v_and_b32_e32 v57, 0xffff0000, v57
	v_mul_f32_e32 v0, v57, v57
	s_waitcnt vmcnt(7)
	v_lshrrev_b32_e32 v61, 8, v63
	v_pk_fma_f32 v[90:91], v[56:57], v[56:57], v[0:1] op_sel_hi:[1,1,0]
	s_waitcnt vmcnt(6)
	v_lshlrev_b32_e32 v0, 24, v67
	v_lshlrev_b32_e32 v35, 16, v66
	v_and_b32_e32 v61, 0xffff00, v61
	v_and_b32_sdwa v63, v62, s8 dst_sel:DWORD dst_unused:UNUSED_PAD src0_sel:WORD_1 src1_sel:DWORD
	v_lshlrev_b32_e32 v60, 8, v62
	v_or_b32_e32 v62, v0, v61
	v_or_b32_e32 v61, v35, v63
	v_and_b32_e32 v63, 0xffffff00, v67
	v_lshlrev_b32_e32 v67, 16, v65
	v_lshlrev_b32_e32 v66, 16, v64
	v_and_b32_e32 v65, 0xffff0000, v65
	v_and_b32_e32 v64, 0xffff0000, v64
	v_pk_mul_f32 v[70:71], v[64:65], v[64:65]
	s_waitcnt vmcnt(5)
	v_lshlrev_b32_e32 v88, 16, v73
	v_pk_fma_f32 v[96:97], v[66:67], v[66:67], v[70:71]
	v_lshl_add_u64 v[70:71], s[0:1], 0, v[40:41]
	v_lshl_add_u64 v[68:69], s[0:1], 0, v[42:43]
	v_and_b32_e32 v89, 0xffff0000, v73
	v_lshlrev_b32_e32 v86, 16, v72
	v_and_b32_e32 v87, 0xffff0000, v72
	v_mov_b32_e32 v100, v90
	v_pk_add_f32 v[96:97], v[96:97], v[96:97] op_sel:[0,1] op_sel_hi:[1,0]
	s_waitcnt vmcnt(4)
	v_lshrrev_b32_e32 v75, 8, v77
	v_lshlrev_b32_e32 v74, 8, v76
	s_waitcnt vmcnt(3)
	v_lshlrev_b32_e32 v0, 24, v79
	v_lshlrev_b32_e32 v35, 16, v78
	v_and_b32_e32 v75, 0xffff00, v75
	v_and_b32_sdwa v76, v76, s8 dst_sel:DWORD dst_unused:UNUSED_PAD src0_sel:WORD_1 src1_sel:DWORD
	v_or_b32_e32 v78, v0, v75
	v_or_b32_e32 v75, v35, v76
	s_waitcnt vmcnt(2)
	v_lshlrev_b32_e32 v85, 16, v80
	v_mov_b32_e32 v101, v85
	v_and_b32_e32 v79, 0xffffff00, v79
	s_waitcnt vmcnt(1)
	v_lshrrev_b32_e32 v73, 8, v167
	s_waitcnt vmcnt(0)
	v_lshlrev_b32_e32 v0, 24, v83
	v_and_b32_e32 v73, 0xffff00, v73
	v_lshlrev_b32_e32 v72, 8, v166
	v_and_b32_sdwa v77, v166, s8 dst_sel:DWORD dst_unused:UNUSED_PAD src0_sel:WORD_1 src1_sel:DWORD
	v_or_b32_e32 v76, v0, v73
	v_mul_f32_e32 v0, v55, v55
	v_lshlrev_b32_e32 v35, 16, v82
	v_pk_fma_f32 v[98:99], v[54:55], v[54:55], v[0:1] op_sel_hi:[1,1,0]
	v_or_b32_e32 v73, v35, v77
	v_and_b32_e32 v77, 0xffffff00, v83
	v_and_b32_e32 v83, 0xffff0000, v80
	v_mov_b32_e32 v84, v98
	v_mul_f32_e32 v35, v83, v83
	v_pk_add_f32 v[90:91], v[98:99], v[90:91]
	v_pk_mul_f32 v[98:99], v[84:85], v[100:101]
	v_mov_b32_e32 v97, v35
	v_mov_b32_e32 v91, v99
	v_mul_f32_e32 v0, v87, v87
	v_lshlrev_b32_e32 v80, 16, v81
	v_and_b32_e32 v81, 0xffff0000, v81
	v_pk_add_f32 v[90:91], v[90:91], v[96:97]
	v_pk_fma_f32 v[96:97], v[86:87], v[86:87], v[0:1] op_sel_hi:[1,1,0]
	v_mul_f32_e32 v0, v89, v89
	v_mul_f32_e32 v82, v80, v80
	v_mul_f32_e32 v102, v81, v81
	v_pk_fma_f32 v[98:99], v[88:89], v[88:89], v[0:1] op_sel_hi:[1,1,0]
	v_and_b32_e32 v0, 64, v230
	v_mov_b32_e32 v97, v82
	v_mov_b32_e32 v99, v102
	v_add_u32_e32 v82, 64, v0
	v_xor_b32_e32 v0, 1, v230
	v_pk_add_f32 v[96:97], v[96:97], v[98:99]
	v_cmp_lt_i32_e32 vcc, v0, v82
	v_pk_add_f32 v[90:91], v[90:91], v[96:97]
	s_nop 0
	v_cndmask_b32_e32 v0, v230, v0, vcc
	v_add_f32_e32 v35, v90, v91
	v_lshlrev_b32_e32 v0, 2, v0
	s_nop 1
	v_add_f32_dpp v84, v35, v35 quad_perm:[1,0,3,2] row_mask:0xf bank_mask:0xf
	v_xor_b32_e32 v35, 2, v230
	v_cmp_lt_i32_e32 vcc, v35, v82
	s_nop 1
	v_cndmask_b32_e32 v35, v230, v35, vcc
	v_lshlrev_b32_e32 v35, 2, v35
	s_nop 1
	v_add_f32_dpp v90, v84, v84 quad_perm:[2,3,0,1] row_mask:0xf bank_mask:0xf
	v_xor_b32_e32 v84, 4, v230
	v_cmp_lt_i32_e32 vcc, v84, v82
	s_nop 1
	v_cndmask_b32_e32 v84, v230, v84, vcc
	v_lshlrev_b32_e32 v84, 2, v84
	s_nop 1
	v_add_f32_dpp v91, v90, v90 row_half_mirror row_mask:0xf bank_mask:0xf
	v_xor_b32_e32 v90, 8, v230
	v_cmp_lt_i32_e32 vcc, v90, v82
	s_nop 1
	v_cndmask_b32_e32 v90, v230, v90, vcc
	v_lshlrev_b32_e32 v90, 2, v90
	s_nop 1
	v_add_f32_dpp v91, v91, v91 row_mirror row_mask:0xf bank_mask:0xf
	v_xor_b32_e32 v96, 16, v230
	v_cmp_lt_i32_e32 vcc, v96, v82
	s_nop 1
	v_cndmask_b32_e32 v96, v230, v96, vcc
	v_lshlrev_b32_e32 v97, 2, v96
	ds_bpermute_b32 v96, v97, v91
	s_waitcnt lgkmcnt(0)
; __device__ __forceinline__ void ew_phase(const Frame& F, const bf16_t* f, const float* gpost, float alpha, const float* hin, float* hout, const float* gpre, bf16_t* xn, ...
;     ...
;         const float rstd = alpha / sqrtf(wave_sum(s) * (1.f / DM) + RMS_EPS);
;         float s2 = 0.f; f32x4* ho = (f32x4*)(hout + (size_t)m * DM) + F.lane;
; #pragma unroll
;         for (int j = 0; j < 4; ++j) { hv[j] = hv[j] + fv[j] * rstd * gp[j]; if (out24) store24(h24 + (size_t)m * (DM * 3), F.lane + 64 * j, hv[j]); else ho[64 * j] = hv[j]; s2 += (hv[j].x * hv[j].x + hv[j].y * hv[j].y) + (hv[j].z * hv[j].z + hv[j].w * hv[j].w); }
;         if (gpre) {
;             const float r2 = 1.0f / sqrtf(wave_sum(s2) * (1.f / DM) + RMS_EPS);
	v_add_f32_e32 v91, v91, v96
	v_xor_b32_e32 v96, 32, v230
	v_cmp_lt_i32_e32 vcc, v96, v82
	s_nop 1
	v_cndmask_b32_e32 v82, v230, v96, vcc
	v_lshlrev_b32_e32 v100, 2, v82
	ds_bpermute_b32 v82, v100, v91
	s_waitcnt lgkmcnt(0)
	v_add_f32_e32 v82, v91, v82
	v_fmamk_f32 v82, v82, 0x3a800000, v225
	v_cmp_gt_f32_e32 vcc, s18, v82
	v_mul_f32_e32 v91, 0x4f800000, v82
	s_nop 0
	v_cndmask_b32_e32 v82, v82, v91, vcc
	v_sqrt_f32_e32 v91, v82
	s_nop 0
	v_add_u32_e32 v96, -1, v91
	v_fma_f32 v98, -v96, v91, v82
	v_cmp_ge_f32_e64 s[0:1], 0, v98
	v_add_u32_e32 v98, 1, v91
	s_nop 0
	v_cndmask_b32_e64 v96, v91, v96, s[0:1]
	v_fma_f32 v91, -v98, v91, v82
	v_cmp_lt_f32_e64 s[0:1], 0, v91
	s_nop 1
	v_cndmask_b32_e64 v91, v96, v98, s[0:1]
	v_mul_f32_e32 v96, 0x37800000, v91
	v_cndmask_b32_e32 v91, v91, v96, vcc
	v_cmp_class_f32_e32 vcc, v82, v226
	s_nop 1
	v_cndmask_b32_e32 v82, v91, v82, vcc
	v_div_scale_f32 v91, s[0:1], v82, v82, 0.5
	v_rcp_f32_e32 v96, v91
	s_mov_b32 s0, 0x7060503
	v_fma_f32 v98, -v91, v96, 1.0
	v_fmac_f32_e32 v96, v98, v96
	v_div_scale_f32 v98, vcc, 0.5, v82, 0.5
	v_mul_f32_e32 v99, v98, v96
	v_fma_f32 v101, -v91, v99, v98
	v_fmac_f32_e32 v99, v101, v96
	v_fma_f32 v91, -v91, v99, v98
	v_div_fmas_f32 v91, v91, v96, v99
	v_div_fixup_f32 v96, v91, v82, 0.5
	v_pk_mul_f32 v[54:55], v[96:97], v[54:55] op_sel_hi:[0,1]
	v_pk_mul_f32 v[56:57], v[96:97], v[56:57] op_sel_hi:[0,1]
	v_pk_fma_f32 v[52:53], v[4:5], v[56:57], v[52:53]
	v_pk_fma_f32 v[50:51], v[2:3], v[54:55], v[50:51]
	v_bfe_u32 v57, v52, 8, 1
	v_bfe_u32 v55, v51, 8, 1
	v_bfe_u32 v54, v50, 8, 1
	v_add3_u32 v55, v51, v55, s15
	v_add3_u32 v57, v52, v57, s15
	v_bfe_u32 v91, v53, 8, 1
	v_add3_u32 v54, v50, v54, s15
	v_lshrrev_b32_e32 v56, 8, v55
	v_lshrrev_b32_e32 v82, 8, v57
	v_add3_u32 v91, v53, v91, s15
	v_alignbit_b32 v54, v56, v54, 8
	v_alignbit_b32 v55, v82, v55, 16
	v_perm_b32 v56, v91, v57, s0
	global_store_dwordx3 v[48:49], v[54:56], off
	v_pk_mul_f32 v[48:49], v[52:53], v[52:53]
	v_mov_b32_e32 v82, v85
	v_pk_mul_f32 v[54:55], v[50:51], v[50:51]
	s_nop 0
	v_pk_mov_b32 v[56:57], v[54:55], v[48:49] op_sel:[1,0]
	v_mov_b32_e32 v55, v49
	v_pk_add_f32 v[48:49], v[54:55], v[56:57]
	s_nop 0
	v_pk_add_f32 v[98:99], v[48:49], v[48:49] op_sel_hi:[0,1]
	v_mov_b32_e32 v48, v66
	v_mov_b32_e32 v49, v64
	v_mov_b32_e32 v64, v67
	v_pk_mul_f32 v[54:55], v[96:97], v[48:49] op_sel_hi:[0,1]
	v_pk_mul_f32 v[48:49], v[96:97], v[64:65] op_sel_hi:[0,1]
	v_pk_fma_f32 v[48:49], v[8:9], v[48:49], v[62:63]
	v_pk_fma_f32 v[54:55], v[6:7], v[54:55], v[60:61]
	v_bfe_u32 v61, v48, 8, 1
	v_bfe_u32 v57, v55, 8, 1
	v_bfe_u32 v56, v54, 8, 1
	v_add3_u32 v57, v55, v57, s15
	v_add3_u32 v62, v48, v61, s15
	v_bfe_u32 v63, v49, 8, 1
	v_add3_u32 v56, v54, v56, s15
	v_lshrrev_b32_e32 v60, 8, v57
	v_lshrrev_b32_e32 v61, 8, v62
	v_add3_u32 v63, v49, v63, s15
	v_alignbit_b32 v60, v60, v56, 8
	v_alignbit_b32 v61, v61, v57, 16
	v_perm_b32 v62, v63, v62, s0
	global_store_dwordx3 v[58:59], v[60:62], off
	v_pk_mul_f32 v[56:57], v[48:49], v[48:49]
	v_pk_mul_f32 v[58:59], v[54:55], v[54:55]
	s_nop 0
	v_pk_mov_b32 v[60:61], v[58:59], v[56:57] op_sel:[1,0]
	v_mov_b32_e32 v59, v57
	v_pk_add_f32 v[56:57], v[58:59], v[60:61]
	v_pk_mul_f32 v[58:59], v[96:97], v[86:87] op_sel_hi:[0,1]
	v_pk_add_f32 v[66:67], v[56:57], v[56:57] op_sel_hi:[0,1]
	v_pk_mul_f32 v[56:57], v[96:97], v[88:89] op_sel_hi:[0,1]
	v_pk_fma_f32 v[56:57], v[20:21], v[56:57], v[78:79]
	v_pk_fma_f32 v[58:59], v[18:19], v[58:59], v[74:75]
	v_bfe_u32 v63, v56, 8, 1
	v_bfe_u32 v61, v59, 8, 1
	v_bfe_u32 v60, v58, 8, 1
	v_add3_u32 v61, v59, v61, s15
	v_add3_u32 v63, v56, v63, s15
	v_bfe_u32 v65, v57, 8, 1
	v_add3_u32 v60, v58, v60, s15
	v_lshrrev_b32_e32 v62, 8, v61
	v_lshrrev_b32_e32 v64, 8, v63
	v_add3_u32 v65, v57, v65, s15
	v_alignbit_b32 v60, v62, v60, 8
	v_alignbit_b32 v61, v64, v61, 16
	v_perm_b32 v62, v65, v63, s0
	global_store_dwordx3 v[70:71], v[60:62], off
	s_nop 1
	v_mul_f32_e32 v60, v58, v58
	v_pk_fma_f32 v[70:71], v[58:59], v[58:59], v[60:61] op_sel_hi:[1,1,0]
	v_mul_f32_e32 v60, v56, v56
	v_pk_fma_f32 v[74:75], v[56:57], v[56:57], v[60:61] op_sel_hi:[1,1,0]
	v_pk_mul_f32 v[62:63], v[82:83], v[96:97] op_sel_hi:[1,0]
	v_pk_mul_f32 v[60:61], v[80:81], v[96:97] op_sel_hi:[1,0]
	v_pk_fma_f32 v[62:63], v[22:23], v[62:63], v[72:73]
	v_pk_fma_f32 v[60:61], v[24:25], v[60:61], v[76:77]
	v_bfe_u32 v65, v63, 8, 1
	v_bfe_u32 v70, v60, 8, 1
	v_bfe_u32 v64, v62, 8, 1
	v_add3_u32 v65, v63, v65, s15
	v_add3_u32 v70, v60, v70, s15
	v_bfe_u32 v73, v61, 8, 1
	v_add3_u32 v64, v62, v64, s15
	v_lshrrev_b32_e32 v66, 8, v65
	v_lshrrev_b32_e32 v72, 8, v70
	v_add3_u32 v73, v61, v73, s15
	v_alignbit_b32 v64, v66, v64, 8
	v_alignbit_b32 v65, v72, v65, 16
	v_perm_b32 v66, v73, v70, s0
	global_store_dwordx3 v[68:69], v[64:66], off
	v_mul_f32_e32 v70, v62, v62
	v_mul_f32_e32 v74, v63, v63
	v_mul_f32_e32 v98, v61, v61
	v_mul_f32_e32 v66, v60, v60
	v_pk_add_f32 v[64:65], v[70:71], v[74:75]
	v_pk_add_f32 v[66:67], v[98:99], v[66:67]
	s_nop 0
	v_pk_add_f32 v[64:65], v[64:65], v[66:67]
	s_nop 0
	v_add_f32_e32 v64, v64, v65
	s_nop 1
	v_add_f32_dpp v0, v64, v64 quad_perm:[1,0,3,2] row_mask:0xf bank_mask:0xf
	s_nop 1
	v_add_f32_dpp v0, v0, v0 quad_perm:[2,3,0,1] row_mask:0xf bank_mask:0xf
	s_nop 1
	v_add_f32_dpp v0, v0, v0 row_half_mirror row_mask:0xf bank_mask:0xf
	s_nop 1
	v_add_f32_dpp v0, v0, v0 row_mirror row_mask:0xf bank_mask:0xf
	ds_bpermute_b32 v35, v97, v0
	s_waitcnt lgkmcnt(0)
; __device__ __forceinline__ unsigned cvt_pk_bf16(float lo, float hi) { f32x2 v = {lo, hi}; bf16x2_t b = __builtin_convertvector(v, bf16x2_t); return __builtin_bit_cast(unsigned, b); }
; __device__ __forceinline__ void ew_phase(const Frame& F, const bf16_t* f, const float* gpost, float alpha, const float* hin, float* hout, const float* gpre, bf16_t* xn, ...
;     ...
;             const float r2 = 1.0f / sqrtf(wave_sum(s2) * (1.f / DM) + RMS_EPS);
;             u32x2* o8 = (u32x2*)(xn + (size_t)m * DM) + F.lane;
; #pragma unroll
;             for (int j = 0; j < 4; ++j) { hv[j] = hv[j] * r2 * gq[j]; u32x2 w; w.x = cvt_pk_bf16(hv[j].x, hv[j].y); w.y = cvt_pk_bf16(hv[j].z, hv[j].w); o8[64 * j] = w; }
	v_add_f32_e32 v0, v0, v35
	ds_bpermute_b32 v35, v100, v0
	s_waitcnt lgkmcnt(0)
	v_add_f32_e32 v0, v0, v35
	v_fmamk_f32 v0, v0, 0x3a800000, v225
	v_cmp_gt_f32_e32 vcc, s18, v0
	v_mul_f32_e32 v35, 0x4f800000, v0
	s_nop 0
	v_cndmask_b32_e32 v0, v0, v35, vcc
	v_sqrt_f32_e32 v35, v0
	s_nop 0
	v_add_u32_e32 v64, -1, v35
	v_fma_f32 v65, -v64, v35, v0
	v_cmp_ge_f32_e64 s[0:1], 0, v65
	v_add_u32_e32 v65, 1, v35
	s_nop 0
	v_cndmask_b32_e64 v64, v35, v64, s[0:1]
	v_fma_f32 v35, -v65, v35, v0
	v_cmp_lt_f32_e64 s[0:1], 0, v35
	s_nop 1
	v_cndmask_b32_e64 v35, v64, v65, s[0:1]
	v_mul_f32_e32 v64, 0x37800000, v35
	v_cndmask_b32_e32 v35, v35, v64, vcc
	v_cmp_class_f32_e32 vcc, v0, v226
	s_nop 1
	v_cndmask_b32_e32 v0, v35, v0, vcc
	v_div_scale_f32 v35, s[0:1], v0, v0, 1.0
	v_rcp_f32_e32 v64, v35
	s_cselect_b64 s[0:1], -1, 0
	v_fma_f32 v65, -v35, v64, 1.0
	v_fmac_f32_e32 v64, v65, v64
	v_div_scale_f32 v65, vcc, 1.0, v0, 1.0
	v_mul_f32_e32 v66, v65, v64
	v_fma_f32 v67, -v35, v66, v65
	v_fmac_f32_e32 v66, v67, v64
	v_fma_f32 v35, -v35, v66, v65
	v_div_fmas_f32 v35, v35, v64, v66
	v_div_fixup_f32 v0, v35, v0, 1.0
	v_pk_mul_f32 v[50:51], v[50:51], v[0:1] op_sel_hi:[1,0]
	v_pk_mul_f32 v[52:53], v[52:53], v[0:1] op_sel_hi:[1,0]
	v_pk_mul_f32 v[50:51], v[10:11], v[50:51]
	v_pk_mul_f32 v[52:53], v[12:13], v[52:53]
	v_lshl_add_u64 v[64:65], v[46:47], 0, s[6:7]
	v_cvt_pk_bf16_f32 v50, v50, v51
	v_cvt_pk_bf16_f32 v51, v52, v53
	global_store_dwordx2 v[64:65], v[50:51], off
	v_pk_mul_f32 v[50:51], v[54:55], v[0:1] op_sel_hi:[1,0]
	v_pk_mul_f32 v[48:49], v[48:49], v[0:1] op_sel_hi:[1,0]
	v_pk_mul_f32 v[50:51], v[14:15], v[50:51]
	v_pk_mul_f32 v[48:49], v[16:17], v[48:49]
	v_cvt_pk_bf16_f32 v50, v50, v51
	v_cvt_pk_bf16_f32 v51, v48, v49
	global_store_dwordx2 v[64:65], v[50:51], off offset:512
	v_pk_mul_f32 v[48:49], v[58:59], v[0:1] op_sel_hi:[1,0]
	v_pk_mul_f32 v[50:51], v[56:57], v[0:1] op_sel_hi:[1,0]
	v_pk_mul_f32 v[48:49], v[26:27], v[48:49]
	v_pk_mul_f32 v[50:51], v[28:29], v[50:51]
	v_cvt_pk_bf16_f32 v48, v48, v49
	v_cvt_pk_bf16_f32 v49, v50, v51
	global_store_dwordx2 v[64:65], v[48:49], off offset:1024
	v_pk_mul_f32 v[48:49], v[62:63], v[0:1] op_sel_hi:[1,0]
	v_pk_mul_f32 v[50:51], v[60:61], v[0:1] op_sel_hi:[1,0]
	v_pk_mul_f32 v[48:49], v[30:31], v[48:49]
	v_pk_mul_f32 v[50:51], v[32:33], v[50:51]
	v_cvt_pk_bf16_f32 v48, v48, v49
	v_cvt_pk_bf16_f32 v49, v50, v51
	global_store_dwordx2 v[64:65], v[48:49], off offset:1536
	s_branch .LBB0_904
